# pass3 swish-gate loads batched (15 serialized global round trips per item removed), GLA table loads batched, convert loads paired
# speedup vs baseline: 1.1161x; 1.0174x over previous
; __device__ __forceinline__ void convert_weights(const KArgs& a, int l, LAS unsigned char* lds) {
;     ...
;         const int kt = r % nkt, rt = r / nkt, r0 = rt * 64, k0 = kt * 64;
;         __syncthreads();
;         if (mode == 1) {
; #pragma unroll
;             for (int e = 0; e < 8; ++e) { const int idx = tid + 512 * e, rl = idx & 63, kl = idx >> 6, rr = r0 + rl, k = k0 + kl;
;                 const int hh = rr / 192, ee = rr % 192; const int col = ee < 128 ? hh * 192 + ee : hh * 192 + 128 + ((ee - 128) & 1) * 32 + ((ee - 128) >> 1);
;                 tile[kl * 65 + rl] = w0[(size_t)k * N + col]; }
;         } else {
; #pragma unroll
;             for (int e = 0; e < 2; ++e) { const int idx = tid + 512 * e, r4 = (idx & 15) * 4, kl = idx >> 4, rr = r0 + r4, k = k0 + kl;
;                 f32x4 v = {0.f, 0.f, 0.f, 0.f};
;                 if (mode == 0) { if (rr < N) v = *(const f32x4*)(w0 + (size_t)k * N + rr); }
;                 else { const int g = rr >> 5, n = (rr >> 4) & 1, i = rr & 15; v = *(const f32x4*)((n ? w1 : w0) + (size_t)k * N + 16 * g + i); }
;                 if (gk) v = v * gk[k];
;                 tile[kl * 65 + r4] = v[0]; tile[kl * 65 + r4 + 1] = v[1]; tile[kl * 65 + r4 + 2] = v[2]; tile[kl * 65 + r4 + 3] = v[3]; }
.LBB0_42:
	v_cvt_f32_u32_e32 v1, s31
	s_sub_i32 s41, 0, s31
	s_abs_i32 s23, s30
	s_ashr_i32 s22, s30, 31
	v_rcp_iflag_f32_e32 v1, v1
	s_waitcnt lgkmcnt(0)
	s_barrier
	v_mul_f32_e32 v1, 0x4f7ffffe, v1
	v_cvt_u32_f32_e32 v1, v1
	s_nop 0
	v_readfirstlane_b32 s42, v1
	s_mul_i32 s41, s41, s42
	s_mul_hi_u32 s41, s42, s41
	s_add_i32 s42, s42, s41
	s_mul_hi_u32 s41, s23, s42
	s_mul_i32 s42, s41, s31
	s_sub_i32 s23, s23, s42
	s_add_i32 s43, s41, 1
	s_sub_i32 s42, s23, s31
	s_cmp_ge_u32 s23, s31
	s_cselect_b32 s41, s43, s41
	s_cselect_b32 s23, s42, s23
	s_add_i32 s42, s41, 1
	s_cmp_ge_u32 s23, s31
	s_cselect_b32 s23, s42, s41
	s_xor_b32 s23, s23, s22
	s_sub_i32 s22, s23, s22
	s_mul_i32 s31, s22, s31
	s_lshl_b32 s23, s22, 6
	s_sub_i32 s22, s30, s31
	s_lshl_b32 s22, s22, 6
	s_mov_b64 s[30:31], -1
	s_and_b64 vcc, exec, s[28:29]
	s_cbranch_vccnz .LBB0_52
	v_mov_b32_e32 v1, s27
	v_mov_b32_e32 v3, s17
	v_or_b32_e32 v2, s23, v14
	v_cndmask_b32_e64 v5, v1, v3, s[4:5]
	v_mov_b32_e32 v1, s26
	v_mov_b32_e32 v3, s16
	v_cndmask_b32_e64 v4, v1, v3, s[4:5]
	v_ashrrev_i32_e32 v1, 1, v2
	v_and_b32_e32 v10, -16, v1
	v_ashrrev_i32_e32 v11, 31, v10
	v_lshl_add_u64 v[4:5], v[10:11], 2, v[4:5]
	v_mov_b32_e32 v7, v0
	v_ashrrev_i32_e32 v3, 31, v2
	v_lshl_add_u64 v[4:5], v[4:5], 0, v[6:7]
	v_cmp_gt_i32_e32 vcc, s40, v2
	v_lshl_add_u64 v[10:11], v[2:3], 2, s[16:17]
	v_mov_b32_e32 v2, v0
	v_mov_b32_e32 v3, v0
	v_add_u32_e32 v12, s22, v18
	v_mov_b32_e32 v1, v0
	v_cndmask_b32_e64 v11, v11, v5, s[24:25]
	v_cndmask_b32_e64 v10, v10, v4, s[24:25]
	v_mov_b64_e32 v[4:5], v[2:3]
	s_or_b64 s[26:27], s[24:25], vcc
	v_ashrrev_i32_e32 v13, 31, v12
	v_mov_b64_e32 v[2:3], v[0:1]
	v_mov_b32_e32 v62, v0
	v_mov_b32_e32 v63, v0
	v_mov_b32_e32 v64, v0
	v_mov_b32_e32 v65, v0
	v_add_u32_e32 v66, s22, v19
	v_ashrrev_i32_e32 v67, 31, v66
	s_and_saveexec_b64 s[24:25], s[26:27]
	s_cbranch_execz .LBB0_45
	v_mad_u64_u32 v[2:3], s[28:29], v12, s40, 0
	v_mov_b32_e32 v4, v3
	v_mad_u64_u32 v[4:5], s[28:29], v13, s40, v[4:5]
	v_mov_b32_e32 v3, v4
	v_lshl_add_u64 v[2:3], v[2:3], 2, v[10:11]
	v_mad_u64_u32 v[62:63], s[28:29], v66, s40, 0
	v_mov_b32_e32 v64, v63
	v_mad_u64_u32 v[64:65], s[28:29], v67, s40, v[64:65]
	v_mov_b32_e32 v63, v64
	v_lshl_add_u64 v[62:63], v[62:63], 2, v[10:11]
	global_load_dwordx4 v[2:5], v[2:3], off
	global_load_dwordx4 v[62:65], v[62:63], off
.LBB0_45:
	s_or_b64 exec, exec, s[24:25]
	s_cmp_eq_u64 s[20:21], 0
	s_cbranch_scc1 .LBB0_47
	v_lshl_add_u64 v[12:13], v[12:13], 2, s[20:21]
	v_lshl_add_u64 v[66:67], v[66:67], 2, s[20:21]
	global_load_dword v12, v[12:13], off
	global_load_dword v66, v[66:67], off
	s_waitcnt vmcnt(0)
	v_pk_mul_f32 v[4:5], v[4:5], v[12:13] op_sel_hi:[1,0]
	v_pk_mul_f32 v[2:3], v[2:3], v[12:13] op_sel_hi:[1,0]
	v_pk_mul_f32 v[64:65], v[64:65], v[66:67] op_sel_hi:[1,0]
	v_pk_mul_f32 v[62:63], v[62:63], v[66:67] op_sel_hi:[1,0]
.LBB0_47:
	s_mov_b64 s[30:31], 0
	s_waitcnt vmcnt(0)
	ds_write2_b32 v28, v2, v3 offset1:1
	ds_write2_b32 v28, v4, v5 offset0:2 offset1:3
	ds_write2_b32 v29, v62, v63 offset1:1
	ds_write2_b32 v29, v64, v65 offset0:2 offset1:3

; __device__ __forceinline__ void convert_weights(const KArgs& a, int l, LAS unsigned char* lds) {
;     ...
;         const int kt = r % nkt, rt = r / nkt, r0 = rt * 64, k0 = kt * 64;
;         __syncthreads();
;         if (mode == 1) {
; #pragma unroll
;             for (int e = 0; e < 8; ++e) { const int idx = tid + 512 * e, rl = idx & 63, kl = idx >> 6, rr = r0 + rl, k = k0 + kl;
;                 const int hh = rr / 192, ee = rr % 192; const int col = ee < 128 ? hh * 192 + ee : hh * 192 + 128 + ((ee - 128) & 1) * 32 + ((ee - 128) >> 1);
;                 tile[kl * 65 + rl] = w0[(size_t)k * N + col]; }
;         } else {
; #pragma unroll
;             for (int e = 0; e < 2; ++e) { const int idx = tid + 512 * e, r4 = (idx & 15) * 4, kl = idx >> 4, rr = r0 + r4, k = k0 + kl;
;                 f32x4 v = {0.f, 0.f, 0.f, 0.f};
;                 if (mode == 0) { if (rr < N) v = *(const f32x4*)(w0 + (size_t)k * N + rr); }
;                 else { const int g = rr >> 5, n = (rr >> 4) & 1, i = rr & 15; v = *(const f32x4*)((n ? w1 : w0) + (size_t)k * N + 16 * g + i); }
;                 if (gk) v = v * gk[k];
;                 tile[kl * 65 + r4] = v[0]; tile[kl * 65 + r4 + 1] = v[1]; tile[kl * 65 + r4 + 2] = v[2]; tile[kl * 65 + r4 + 3] = v[3]; }
.LBB0_129:
	v_cvt_f32_u32_e32 v0, s37
	s_sub_i32 s40, 0, s37
	s_abs_i32 s29, s36
	s_ashr_i32 s28, s36, 31
	v_rcp_iflag_f32_e32 v0, v0
	s_movk_i32 s2, 0x2a00
	s_barrier
	v_mul_f32_e32 v0, 0x4f7ffffe, v0
	v_cvt_u32_f32_e32 v0, v0
	s_nop 0
	v_readfirstlane_b32 s41, v0
	s_mul_i32 s40, s40, s41
	s_mul_hi_u32 s40, s41, s40
	s_add_i32 s41, s41, s40
	s_mul_hi_u32 s40, s29, s41
	s_mul_i32 s41, s40, s37
	s_sub_i32 s29, s29, s41
	s_add_i32 s42, s40, 1
	s_sub_i32 s41, s29, s37
	s_cmp_ge_u32 s29, s37
	s_cselect_b32 s40, s42, s40
	s_cselect_b32 s29, s41, s29
	s_add_i32 s41, s40, 1
	s_cmp_ge_u32 s29, s37
	s_cselect_b32 s29, s41, s40
	s_xor_b32 s29, s29, s28
	s_sub_i32 s28, s29, s28
	s_mul_i32 s37, s28, s37
	s_lshl_b32 s29, s28, 6
	s_sub_i32 s28, s36, s37
	s_lshl_b32 s28, s28, 6
	s_mov_b64 s[36:37], -1
	s_and_b64 vcc, exec, s[34:35]
	s_cbranch_vccnz .LBB0_139
	v_mov_b32_e32 v1, s31
	v_mov_b32_e32 v2, s23
	v_or_b32_e32 v0, s29, v12
	v_cndmask_b32_e64 v3, v1, v2, s[4:5]
	v_mov_b32_e32 v1, s30
	v_mov_b32_e32 v2, s22
	v_cndmask_b32_e64 v2, v1, v2, s[4:5]
	v_ashrrev_i32_e32 v1, 1, v0
	v_and_b32_e32 v8, -16, v1
	v_ashrrev_i32_e32 v9, 31, v8
	v_lshl_add_u64 v[2:3], v[8:9], 2, v[2:3]
	v_mov_b32_e32 v5, v113
	v_ashrrev_i32_e32 v1, 31, v0
	v_lshl_add_u64 v[2:3], v[2:3], 0, v[4:5]
	v_cmp_gt_i32_e32 vcc, s39, v0
	v_lshl_add_u64 v[0:1], v[0:1], 2, s[22:23]
	v_mov_b32_e32 v112, v113
	v_add_u32_e32 v10, s28, v16
	v_mov_b32_e32 v114, v113
	v_mov_b32_e32 v115, v113
	v_cndmask_b32_e64 v9, v1, v3, s[26:27]
	v_cndmask_b32_e64 v8, v0, v2, s[26:27]
	v_mov_b64_e32 v[0:1], v[112:113]
	s_or_b64 s[30:31], s[26:27], vcc
	v_ashrrev_i32_e32 v11, 31, v10
	v_mov_b64_e32 v[2:3], v[114:115]
	v_mov_b32_e32 v62, v113
	v_mov_b32_e32 v63, v113
	v_mov_b32_e32 v64, v113
	v_mov_b32_e32 v65, v113
	v_add_u32_e32 v66, s28, v17
	v_ashrrev_i32_e32 v67, 31, v66
	s_and_saveexec_b64 s[26:27], s[30:31]
	s_cbranch_execz .LBB0_132
	v_mad_u64_u32 v[0:1], s[34:35], v10, s39, 0
	v_mov_b32_e32 v2, v1
	v_mad_u64_u32 v[2:3], s[34:35], v11, s39, v[2:3]
	v_mov_b32_e32 v1, v2
	v_lshl_add_u64 v[0:1], v[0:1], 2, v[8:9]
	v_mad_u64_u32 v[62:63], s[34:35], v66, s39, 0
	v_mov_b32_e32 v64, v63
	v_mad_u64_u32 v[64:65], s[34:35], v67, s39, v[64:65]
	v_mov_b32_e32 v63, v64
	v_lshl_add_u64 v[62:63], v[62:63], 2, v[8:9]
	global_load_dwordx4 v[0:3], v[0:1], off
	global_load_dwordx4 v[62:65], v[62:63], off
.LBB0_132:
	s_or_b64 exec, exec, s[26:27]
	s_cmp_eq_u64 s[24:25], 0
	s_cbranch_scc1 .LBB0_134
	v_lshl_add_u64 v[10:11], v[10:11], 2, s[24:25]
	v_lshl_add_u64 v[66:67], v[66:67], 2, s[24:25]
	global_load_dword v10, v[10:11], off
	global_load_dword v66, v[66:67], off
	s_waitcnt vmcnt(0)
	v_pk_mul_f32 v[2:3], v[2:3], v[10:11] op_sel_hi:[1,0]
	v_pk_mul_f32 v[0:1], v[0:1], v[10:11] op_sel_hi:[1,0]
	v_pk_mul_f32 v[64:65], v[64:65], v[66:67] op_sel_hi:[1,0]
	v_pk_mul_f32 v[62:63], v[62:63], v[66:67] op_sel_hi:[1,0]
.LBB0_134:
	v_mov_b32_e32 v112, v113
	v_mov_b32_e32 v114, v113
	v_mov_b32_e32 v115, v113
	s_mov_b64 s[36:37], 0
	s_waitcnt vmcnt(0)
	ds_write2_b32 v26, v0, v1 offset1:1
	ds_write2_b32 v26, v2, v3 offset0:2 offset1:3
	ds_write2_b32 v27, v62, v63 offset1:1
	ds_write2_b32 v27, v64, v65 offset0:2 offset1:3

; template <int TYPE>
; __device__ __forceinline__ LgRaw lg_issue(const bf16_t* u, int h, int dir, size_t tok0, int tid) {
;     ...
;         const int i = tid >> 3, d8 = tid & 7; const bf16_t* ur = u + (tok0 + i) * DINP;
;         r.a0 = *(const bf16x8*)(ur + (dir ? C_GAB : C_GAF)); r.a1 = *(const bf16x8*)(ur + (dir ? C_GAB : C_GAF) + 8); r.k = *(const bf16x8*)(ur + C_GK + h * 64 + d8 * 8);
; template <int TYPE>
; __device__ __forceinline__ void lg_compute(const KArgs& a, unsigned char* wsb, int l, int h, int dir, const LgRaw& raw, LAS unsigned char* lds, int tid) {
;     ...
;         const int i = tid >> 3, d8 = tid & 7;
;         float ua[16]; unpack8(raw.a0, ua); unpack8(raw.a1, ua + 8);
;         const float* up = (const float*)a.in[3] + (size_t)((l * 2 + dir) * 16) * 256 + h * 64 + d8 * 8;
;         const float* bs = (const float*)a.in[4] + (l * 2 + dir) * 256 + h * 64 + d8 * 8;
;         f32x4 z0 = *(const f32x4*)bs, z1 = *(const f32x4*)(bs + 4);
; #pragma unroll
;         for (int r = 0; r < 16; ++r) { z0 += ua[r] * *(const f32x4*)(up + r * 256); z1 += ua[r] * *(const f32x4*)(up + r * 256 + 4); }
.LBB0_288:
	s_ashr_i32 s4, s16, 11
	s_ashr_i32 s5, s4, 31
	s_lshl_b64 s[4:5], s[4:5], 14
	s_and_b32 s6, s15, 0x3fc0
	s_mov_b64 s[12:13], s[68:69]
	v_mov_b32_e32 v12, v195
	s_bfe_i32 s18, s16, 0x10008
	s_bfe_u32 s17, s16, 0x10008
	s_bfe_u32 s19, s16, 0x20009
	s_or_b32 s4, s4, s6
	s_add_u32 s6, s12, 0xe300000
	v_ashrrev_i32_e32 v8, 3, v12
	s_addc_u32 s7, s13, 0
	v_ashrrev_i32_e32 v9, 31, v8
	v_lshl_add_u64 v[0:1], s[4:5], 0, v[8:9]
	v_mov_b64_e32 v[2:3], s[6:7]
	v_mad_u64_u32 v[2:3], s[20:21], v0, s2, v[2:3]
	s_mulk_i32 s5, 0x2a00
	s_mul_hi_u32 s21, s4, 0x2a00
	s_lshl_b32 s20, s19, 7
	s_add_i32 s21, s21, s5
	s_mulk_i32 s4, 0x2a00
	s_add_u32 s4, s6, s4
	s_addc_u32 s5, s7, s21
	s_lshl_b32 s19, s19, 8
	s_add_u32 s4, s4, s19
	s_addc_u32 s5, s5, 0
	s_or_b32 s21, s17, s14
	s_lshl_b32 s72, s21, 12
	v_readlane_b32 s36, v253, 48
	s_lshl_b64 s[6:7], s[72:73], 2
	v_readlane_b32 s42, v253, 54
	v_readlane_b32 s43, v253, 55
	s_add_u32 s6, s42, s6
	s_addc_u32 s7, s43, s7
	s_add_u32 s6, s6, s19
	s_addc_u32 s7, s7, 0
	s_lshl_b32 s72, s21, 8
	v_readlane_b32 s44, v253, 56
	s_lshl_b64 s[22:23], s[72:73], 2
	v_readlane_b32 s45, v253, 57
	s_add_u32 s21, s44, s22
	s_addc_u32 s23, s45, s23
	s_add_u32 s22, s21, s19
	s_addc_u32 s23, s23, 0
	s_add_i32 s19, s17, 3
	s_cmp_eq_u32 s17, 0
	s_cselect_b64 vcc, -1, 0
	s_and_b64 s[24:25], vcc, exec
	s_movk_i32 s21, 0x820
	v_lshlrev_b32_e32 v9, 3, v12
	v_mad_i32_i24 v3, v1, s2, v3
	s_cselect_b32 s72, 0x800, s21
	s_mov_b32 s21, s73
	v_and_b32_e32 v13, 56, v9
	v_ashrrev_i32_e32 v35, 4, v12
	s_movk_i32 s2, 0x2a00
	v_lshl_add_u64 v[0:1], v[2:3], 0, s[20:21]
	v_lshlrev_b32_e32 v112, 1, v13
	v_mov_b64_e32 v[6:7], s[4:5]
	v_and_b32_e32 v37, 0x78, v9
	v_add_u32_e32 v16, 32, v35
	v_lshl_add_u64 v[10:11], v[2:3], 0, s[72:73]
	v_lshl_add_u64 v[0:1], v[0:1], 0, v[112:113]
	v_mad_i64_i32 v[4:5], s[4:5], v35, s2, v[6:7]
	v_lshlrev_b32_e32 v14, 1, v37
	v_mov_b32_e32 v15, v113
	v_mad_i64_i32 v[6:7], s[4:5], v16, s2, v[6:7]
	s_waitcnt lgkmcnt(0)
	s_barrier
	global_load_dwordx4 v[0:3], v[0:1], off offset:512
	v_lshl_add_u64 v[4:5], v[4:5], 0, v[14:15]
	v_lshl_add_u64 v[6:7], v[6:7], 0, v[14:15]
	global_load_dwordx4 v[14:17], v[10:11], off
	global_load_dwordx4 v[64:67], v[10:11], off offset:16
	v_lshlrev_b32_e32 v68, 2, v13
	v_add_u32_e32 v69, 0x1000, v68
	v_add_u32_e32 v94, 0x2000, v68
	v_add_u32_e32 v95, 0x3000, v68
	s_mov_b64 s[4:5], 0x1000
	s_movk_i32 s0, 0x3000
	s_mov_b32 s20, 0xbfb8aa3b
	s_movk_i32 s93, 0x110
	v_readlane_b32 s37, v253, 49
	v_readlane_b32 s38, v253, 50
	v_readlane_b32 s39, v253, 51
	v_readlane_b32 s40, v253, 52
	v_readlane_b32 s41, v253, 53
	v_readlane_b32 s46, v253, 58
	v_readlane_b32 s47, v253, 59
	v_readlane_b32 s48, v253, 60
	v_readlane_b32 s49, v253, 61
	v_readlane_b32 s50, v253, 62
	v_readlane_b32 s51, v253, 63
	global_load_dwordx4 v[70:73], v68, s[22:23] offset:16
	global_load_dwordx4 v[74:77], v68, s[22:23]
	global_load_dwordx4 v[114:117], v68, s[6:7] offset:16
	global_load_dwordx4 v[118:121], v68, s[6:7]
	global_load_dwordx4 v[122:125], v68, s[6:7] offset:1040
	global_load_dwordx4 v[126:129], v68, s[6:7] offset:1024
	global_load_dwordx4 v[130:133], v68, s[6:7] offset:2064
	global_load_dwordx4 v[134:137], v68, s[6:7] offset:2048
	global_load_dwordx4 v[138:141], v68, s[6:7] offset:3088
	global_load_dwordx4 v[142:145], v68, s[6:7] offset:3072
	global_load_dwordx4 v[146:149], v69, s[6:7] offset:16
	global_load_dwordx4 v[150:153], v69, s[6:7]
	global_load_dwordx4 v[154:157], v69, s[6:7] offset:1040
	global_load_dwordx4 v[158:161], v69, s[6:7] offset:1024
	global_load_dwordx4 v[162:165], v69, s[6:7] offset:2064
	global_load_dwordx4 v[166:169], v69, s[6:7] offset:2048
	global_load_dwordx4 v[170:173], v69, s[6:7] offset:3088
	global_load_dwordx4 v[174:177], v69, s[6:7] offset:3072
	global_load_dwordx4 v[178:181], v94, s[6:7] offset:16
	global_load_dwordx4 v[182:185], v94, s[6:7]
	global_load_dwordx4 v[186:189], v94, s[6:7] offset:1040
	global_load_dwordx4 v[190:193], v94, s[6:7] offset:1024
	global_load_dwordx4 v[202:205], v94, s[6:7] offset:2064
	global_load_dwordx4 v[206:209], v94, s[6:7] offset:2048
	global_load_dwordx4 v[210:213], v94, s[6:7] offset:3088
	global_load_dwordx4 v[214:217], v94, s[6:7] offset:3072
	global_load_dwordx4 v[218:221], v95, s[6:7] offset:16
	global_load_dwordx4 v[222:225], v95, s[6:7]
	global_load_dwordx4 v[226:229], v95, s[6:7] offset:1040
	global_load_dwordx4 v[230:233], v95, s[6:7] offset:1024
	global_load_dwordx4 v[78:81], v95, s[6:7] offset:2064
	global_load_dwordx4 v[82:85], v95, s[6:7] offset:2048
	global_load_dwordx4 v[86:89], v95, s[6:7] offset:3088
	global_load_dwordx4 v[90:93], v95, s[6:7] offset:3072
	s_waitcnt vmcnt(0) lgkmcnt(0)
; __device__ __forceinline__ float logsigmoid_(float z) { return fminf(z, 0.f) - __logf(1.f + __expf(-fabsf(z))); }
; template <int TYPE>
; __device__ __forceinline__ void lg_compute(const KArgs& a, unsigned char* wsb, int l, int h, int dir, const LgRaw& raw, LAS unsigned char* lds, int tid) {
;     ...
;         float ua[16]; unpack8(raw.a0, ua); unpack8(raw.a1, ua + 8);
;         const float* up = (const float*)a.in[3] + (size_t)((l * 2 + dir) * 16) * 256 + h * 64 + d8 * 8;
;         const float* bs = (const float*)a.in[4] + (l * 2 + dir) * 256 + h * 64 + d8 * 8;
;         f32x4 z0 = *(const f32x4*)bs, z1 = *(const f32x4*)(bs + 4);
; #pragma unroll
;         for (int r = 0; r < 16; ++r) { z0 += ua[r] * *(const f32x4*)(up + r * 256); z1 += ua[r] * *(const f32x4*)(up + r * 256 + 4); }
;         f32x4 g0, g1;
; #pragma unroll
;         for (int e = 0; e < 4; ++e) { g0[e] = logsigmoid_(z0[e]) * (1.f / 16.f); g1[e] = logsigmoid_(z1[e]) * (1.f / 16.f); }
	v_lshlrev_b32_e32 v30, 16, v14
	v_and_b32_e32 v32, 0xffff0000, v14
	v_lshlrev_b32_e32 v34, 16, v15
	v_and_b32_e32 v36, 0xffff0000, v15
	v_lshlrev_b32_e32 v38, 16, v16
	v_and_b32_e32 v40, 0xffff0000, v16
	v_lshlrev_b32_e32 v42, 16, v17
	v_and_b32_e32 v44, 0xffff0000, v17
	v_lshlrev_b32_e32 v10, 2, v13
	v_mov_b32_e32 v11, v113
	v_lshlrev_b32_e32 v46, 16, v64
	v_and_b32_e32 v48, 0xffff0000, v64
	v_lshlrev_b32_e32 v50, 16, v65
	v_and_b32_e32 v52, 0xffff0000, v65
	v_lshlrev_b32_e32 v54, 16, v66
	v_and_b32_e32 v56, 0xffff0000, v66
	v_lshlrev_b32_e32 v58, 16, v67
	v_and_b32_e32 v60, 0xffff0000, v67
	v_pk_fma_f32 v[22:23], v[30:31], v[114:115], v[70:71] op_sel_hi:[0,1,1]
	v_pk_fma_f32 v[24:25], v[30:31], v[116:117], v[72:73] op_sel_hi:[0,1,1]
	v_pk_fma_f32 v[26:27], v[30:31], v[118:119], v[74:75] op_sel_hi:[0,1,1]
	v_pk_fma_f32 v[28:29], v[30:31], v[120:121], v[76:77] op_sel_hi:[0,1,1]
	v_pk_fma_f32 v[22:23], v[32:33], v[122:123], v[22:23] op_sel_hi:[0,1,1]
	v_pk_fma_f32 v[24:25], v[32:33], v[124:125], v[24:25] op_sel_hi:[0,1,1]
	v_pk_fma_f32 v[26:27], v[32:33], v[126:127], v[26:27] op_sel_hi:[0,1,1]
	v_pk_fma_f32 v[28:29], v[32:33], v[128:129], v[28:29] op_sel_hi:[0,1,1]
	v_pk_fma_f32 v[22:23], v[34:35], v[130:131], v[22:23] op_sel_hi:[0,1,1]
	v_pk_fma_f32 v[24:25], v[34:35], v[132:133], v[24:25] op_sel_hi:[0,1,1]
	v_pk_fma_f32 v[26:27], v[34:35], v[134:135], v[26:27] op_sel_hi:[0,1,1]
	v_pk_fma_f32 v[28:29], v[34:35], v[136:137], v[28:29] op_sel_hi:[0,1,1]
	v_pk_fma_f32 v[22:23], v[36:37], v[138:139], v[22:23] op_sel_hi:[0,1,1]
	v_pk_fma_f32 v[24:25], v[36:37], v[140:141], v[24:25] op_sel_hi:[0,1,1]
	v_pk_fma_f32 v[26:27], v[36:37], v[142:143], v[26:27] op_sel_hi:[0,1,1]
	v_pk_fma_f32 v[28:29], v[36:37], v[144:145], v[28:29] op_sel_hi:[0,1,1]
	v_pk_fma_f32 v[22:23], v[38:39], v[146:147], v[22:23] op_sel_hi:[0,1,1]
	v_pk_fma_f32 v[24:25], v[38:39], v[148:149], v[24:25] op_sel_hi:[0,1,1]
	v_pk_fma_f32 v[26:27], v[38:39], v[150:151], v[26:27] op_sel_hi:[0,1,1]
	v_pk_fma_f32 v[28:29], v[38:39], v[152:153], v[28:29] op_sel_hi:[0,1,1]
	v_pk_fma_f32 v[22:23], v[40:41], v[154:155], v[22:23] op_sel_hi:[0,1,1]
	v_pk_fma_f32 v[24:25], v[40:41], v[156:157], v[24:25] op_sel_hi:[0,1,1]
	v_pk_fma_f32 v[26:27], v[40:41], v[158:159], v[26:27] op_sel_hi:[0,1,1]
	v_pk_fma_f32 v[28:29], v[40:41], v[160:161], v[28:29] op_sel_hi:[0,1,1]
	v_pk_fma_f32 v[22:23], v[42:43], v[162:163], v[22:23] op_sel_hi:[0,1,1]
	v_pk_fma_f32 v[24:25], v[42:43], v[164:165], v[24:25] op_sel_hi:[0,1,1]
	v_pk_fma_f32 v[26:27], v[42:43], v[166:167], v[26:27] op_sel_hi:[0,1,1]
	v_pk_fma_f32 v[28:29], v[42:43], v[168:169], v[28:29] op_sel_hi:[0,1,1]
	v_pk_fma_f32 v[22:23], v[44:45], v[170:171], v[22:23] op_sel_hi:[0,1,1]
	v_pk_fma_f32 v[24:25], v[44:45], v[172:173], v[24:25] op_sel_hi:[0,1,1]
	v_pk_fma_f32 v[26:27], v[44:45], v[174:175], v[26:27] op_sel_hi:[0,1,1]
	v_pk_fma_f32 v[28:29], v[44:45], v[176:177], v[28:29] op_sel_hi:[0,1,1]
	v_pk_fma_f32 v[22:23], v[46:47], v[178:179], v[22:23] op_sel_hi:[0,1,1]
	v_pk_fma_f32 v[24:25], v[46:47], v[180:181], v[24:25] op_sel_hi:[0,1,1]
	v_pk_fma_f32 v[26:27], v[46:47], v[182:183], v[26:27] op_sel_hi:[0,1,1]
	v_pk_fma_f32 v[28:29], v[46:47], v[184:185], v[28:29] op_sel_hi:[0,1,1]
	v_pk_fma_f32 v[22:23], v[48:49], v[186:187], v[22:23] op_sel_hi:[0,1,1]
	v_pk_fma_f32 v[24:25], v[48:49], v[188:189], v[24:25] op_sel_hi:[0,1,1]
	v_pk_fma_f32 v[26:27], v[48:49], v[190:191], v[26:27] op_sel_hi:[0,1,1]
	v_pk_fma_f32 v[28:29], v[48:49], v[192:193], v[28:29] op_sel_hi:[0,1,1]
	v_pk_fma_f32 v[22:23], v[50:51], v[202:203], v[22:23] op_sel_hi:[0,1,1]
	v_pk_fma_f32 v[24:25], v[50:51], v[204:205], v[24:25] op_sel_hi:[0,1,1]
	v_pk_fma_f32 v[26:27], v[50:51], v[206:207], v[26:27] op_sel_hi:[0,1,1]
	v_pk_fma_f32 v[28:29], v[50:51], v[208:209], v[28:29] op_sel_hi:[0,1,1]
	v_pk_fma_f32 v[22:23], v[52:53], v[210:211], v[22:23] op_sel_hi:[0,1,1]
	v_pk_fma_f32 v[24:25], v[52:53], v[212:213], v[24:25] op_sel_hi:[0,1,1]
	v_pk_fma_f32 v[26:27], v[52:53], v[214:215], v[26:27] op_sel_hi:[0,1,1]
	v_pk_fma_f32 v[28:29], v[52:53], v[216:217], v[28:29] op_sel_hi:[0,1,1]
	v_pk_fma_f32 v[22:23], v[54:55], v[218:219], v[22:23] op_sel_hi:[0,1,1]
	v_pk_fma_f32 v[24:25], v[54:55], v[220:221], v[24:25] op_sel_hi:[0,1,1]
	v_pk_fma_f32 v[26:27], v[54:55], v[222:223], v[26:27] op_sel_hi:[0,1,1]
	v_pk_fma_f32 v[28:29], v[54:55], v[224:225], v[28:29] op_sel_hi:[0,1,1]
	v_pk_fma_f32 v[22:23], v[56:57], v[226:227], v[22:23] op_sel_hi:[0,1,1]
	v_pk_fma_f32 v[24:25], v[56:57], v[228:229], v[24:25] op_sel_hi:[0,1,1]
	v_pk_fma_f32 v[26:27], v[56:57], v[230:231], v[26:27] op_sel_hi:[0,1,1]
	v_pk_fma_f32 v[28:29], v[56:57], v[232:233], v[28:29] op_sel_hi:[0,1,1]
	v_pk_fma_f32 v[22:23], v[58:59], v[78:79], v[22:23] op_sel_hi:[0,1,1]
	v_pk_fma_f32 v[24:25], v[58:59], v[80:81], v[24:25] op_sel_hi:[0,1,1]
	v_pk_fma_f32 v[26:27], v[58:59], v[82:83], v[26:27] op_sel_hi:[0,1,1]
	v_pk_fma_f32 v[28:29], v[58:59], v[84:85], v[28:29] op_sel_hi:[0,1,1]
	v_pk_fma_f32 v[14:15], v[60:61], v[90:91], v[26:27] op_sel_hi:[0,1,1]
	v_pk_fma_f32 v[16:17], v[60:61], v[92:93], v[28:29] op_sel_hi:[0,1,1]
	v_pk_fma_f32 v[18:19], v[60:61], v[86:87], v[22:23] op_sel_hi:[0,1,1]
	v_pk_fma_f32 v[20:21], v[60:61], v[88:89], v[24:25] op_sel_hi:[0,1,1]
	s_mov_b32 s0, 0x3d800000
	v_mul_f32_e64 v11, |v14|, s20
	v_exp_f32_e32 v11, v11
	v_min_f32_e32 v22, 0, v14
	v_add_f32_e32 v11, 1.0, v11
	v_cmp_gt_f32_e64 s[4:5], s33, v11
	v_min_f32_e32 v24, 0, v18
	v_min_f32_e32 v23, 0, v15
	v_cndmask_b32_e64 v14, 0, 32, s[4:5]
	v_ldexp_f32 v11, v11, v14
	v_log_f32_e32 v11, v11
	v_min_f32_e32 v25, 0, v19
	v_min_f32_e32 v26, 0, v16
; #define LAS __attribute__((address_space(3)))
; __device__ __forceinline__ float logsigmoid_(float z) { return fminf(z, 0.f) - __logf(1.f + __expf(-fabsf(z))); }
; template <int TYPE>
; __device__ __forceinline__ void lg_compute(const KArgs& a, unsigned char* wsb, int l, int h, int dir, const LgRaw& raw, LAS unsigned char* lds, int tid) {
;     ...
;         for (int e = 0; e < 4; ++e) { g0[e] = logsigmoid_(z0[e]) * (1.f / 16.f); g1[e] = logsigmoid_(z1[e]) * (1.f / 16.f); }
;         *(LAS f32x4*)(G + i * C::LDG + d8 * 8) = g0; *(LAS f32x4*)(G + i * C::LDG + d8 * 8 + 4) = g1;
;         *(LAS bf16x8*)(Kb + i * C::LDK_ + d8 * 8) = raw.k;
;     }
; }
; template <int TYPE>
; __device__ __forceinline__ void cumsum_g(int dir, LAS unsigned char* lds, int tid) {
;     using C = Cfg<TYPE>; constexpr int NSEG = 512 / C::DK, SEGL = 64 / NSEG;
;     LAS float* G = (LAS float*)(lds + SC_G); LAS float* SG = (LAS float*)(lds + SC_SEG);
;     const int d = tid % C::DK, seg = tid / C::DK;
;     __syncthreads();
;     float run = 0.f;
; #pragma unroll
;     for (int ii = 0; ii < SEGL; ++ii) { const int i = seg * SEGL + (dir ? SEGL - 1 - ii : ii); run += G[i * C::LDG + d]; G[i * C::LDG + d] = run; }
;     SG[seg * 128 + d] = run;
;     __syncthreads();
;     float off = 0.f;
; #pragma unroll
;     for (int s = 0; s < NSEG; ++s) { const bool before = dir ? (s > seg) : (s < seg); if (before) off += SG[s * 128 + d]; }
; #pragma unroll
;     for (int ii = 0; ii < SEGL; ++ii) { const int i = seg * SEGL + ii; G[i * C::LDG + d] += off; }
;     __syncthreads();
; }
; __device__ __forceinline__ void vT_write(const VRaw& r, LAS unsigned char* lds, int tid) {
;     LAS bf16_t* VT = (LAS bf16_t*)(lds + SC_VT);
;     const int v8 = tid & 15;
; #pragma unroll
;     for (int e2 = 0; e2 < 2; ++e2) { const int i = (tid >> 4) + 32 * e2; const bf16x8 x = e2 ? r.x1 : r.x0; const int pc = ((((i >> 3) ^ (v8 & 7)) << 3) | (i & 7));
; #pragma unroll
;         for (int e = 0; e < 8; ++e) VT[(v8 * 8 + e) * LDT + pc] = (bf16_t)x[e]; }
; }
	v_mul_f32_e32 v14, 0x3f317217, v11
	v_fma_f32 v14, v11, s92, -v14
	v_fmac_f32_e32 v14, 0x3377d1cf, v11
	v_fmac_f32_e32 v14, 0x3f317217, v11
	v_cmp_lt_f32_e64 s[6:7], |v11|, s90
	v_min_f32_e32 v28, 0, v20
	v_min_f32_e32 v27, 0, v17
	v_cndmask_b32_e64 v11, v11, v14, s[6:7]
	v_cndmask_b32_e64 v14, 0, v238, s[4:5]
	v_sub_f32_e32 v14, v11, v14
	v_mul_f32_e64 v11, |v18|, s20
	v_exp_f32_e32 v11, v11
	v_min_f32_e32 v29, 0, v21
	v_add_f32_e32 v11, 1.0, v11
	v_cmp_gt_f32_e64 s[4:5], s33, v11
	s_nop 1
	v_cndmask_b32_e64 v18, 0, 32, s[4:5]
	v_ldexp_f32 v11, v11, v18
	v_log_f32_e32 v11, v11
	s_nop 0
	v_mul_f32_e32 v18, 0x3f317217, v11
	v_fma_f32 v18, v11, s92, -v18
	v_fmac_f32_e32 v18, 0x3377d1cf, v11
	v_fmac_f32_e32 v18, 0x3f317217, v11
	v_cmp_lt_f32_e64 s[6:7], |v11|, s90
	s_nop 1
	v_cndmask_b32_e64 v11, v11, v18, s[6:7]
	v_cndmask_b32_e64 v18, 0, v238, s[4:5]
	v_sub_f32_e32 v18, v11, v18
	v_mul_f32_e64 v11, |v15|, s20
	v_exp_f32_e32 v11, v11
	s_nop 0
	v_add_f32_e32 v11, 1.0, v11
	v_cmp_gt_f32_e64 s[4:5], s33, v11
	s_nop 1
	v_cndmask_b32_e64 v15, 0, 32, s[4:5]
	v_ldexp_f32 v11, v11, v15
	v_log_f32_e32 v11, v11
	s_nop 0
	v_mul_f32_e32 v15, 0x3f317217, v11
	v_fma_f32 v15, v11, s92, -v15
	v_fmac_f32_e32 v15, 0x3377d1cf, v11
	v_fmac_f32_e32 v15, 0x3f317217, v11
	v_cmp_lt_f32_e64 s[6:7], |v11|, s90
	s_nop 1
	v_cndmask_b32_e64 v11, v11, v15, s[6:7]
	v_cndmask_b32_e64 v15, 0, v238, s[4:5]
	v_sub_f32_e32 v15, v11, v15
	v_mul_f32_e64 v11, |v19|, s20
	v_exp_f32_e32 v11, v11
	v_pk_add_f32 v[14:15], v[22:23], v[14:15] neg_lo:[0,1] neg_hi:[0,1]
	v_add_f32_e32 v11, 1.0, v11
	v_cmp_gt_f32_e64 s[4:5], s33, v11
	v_pk_mul_f32 v[14:15], v[14:15], s[0:1] op_sel_hi:[1,0]
	s_nop 0
	v_cndmask_b32_e64 v19, 0, 32, s[4:5]
	v_ldexp_f32 v11, v11, v19
	v_log_f32_e32 v11, v11
	s_nop 0
	v_mul_f32_e32 v19, 0x3f317217, v11
	v_fma_f32 v19, v11, s92, -v19
	v_fmac_f32_e32 v19, 0x3377d1cf, v11
	v_fmac_f32_e32 v19, 0x3f317217, v11
	v_cmp_lt_f32_e64 s[6:7], |v11|, s90
	s_nop 1
	v_cndmask_b32_e64 v11, v11, v19, s[6:7]
	v_cndmask_b32_e64 v19, 0, v238, s[4:5]
	v_sub_f32_e32 v19, v11, v19
	v_mul_f32_e64 v11, |v16|, s20
	v_exp_f32_e32 v11, v11
	v_pk_add_f32 v[18:19], v[24:25], v[18:19] neg_lo:[0,1] neg_hi:[0,1]
	global_load_dwordx4 v[22:25], v[4:5], off offset:1024
	s_nop 0
	global_load_dwordx4 v[4:7], v[6:7], off offset:1024
	v_pk_mul_f32 v[18:19], v[18:19], s[0:1] op_sel_hi:[1,0]
	v_add_f32_e32 v11, 1.0, v11
	v_cmp_gt_f32_e64 s[4:5], s33, v11
	s_nop 1
	v_cndmask_b32_e64 v16, 0, 32, s[4:5]
	v_ldexp_f32 v11, v11, v16
	v_log_f32_e32 v11, v11
	s_nop 0
	v_mul_f32_e32 v16, 0x3f317217, v11
	v_fma_f32 v16, v11, s92, -v16
	v_fmac_f32_e32 v16, 0x3377d1cf, v11
	v_fmac_f32_e32 v16, 0x3f317217, v11
	v_cmp_lt_f32_e64 s[6:7], |v11|, s90
	s_nop 1
	v_cndmask_b32_e64 v11, v11, v16, s[6:7]
	v_cndmask_b32_e64 v16, 0, v238, s[4:5]
	v_sub_f32_e32 v16, v11, v16
	v_mul_f32_e64 v11, |v20|, s20
	v_exp_f32_e32 v11, v11
	s_nop 0
	v_add_f32_e32 v11, 1.0, v11
	v_cmp_gt_f32_e64 s[4:5], s33, v11
	s_nop 1
	v_cndmask_b32_e64 v20, 0, 32, s[4:5]
	v_ldexp_f32 v11, v11, v20
	v_log_f32_e32 v11, v11
	s_nop 0
	v_mul_f32_e32 v20, 0x3f317217, v11
	v_fma_f32 v20, v11, s92, -v20
	v_fmac_f32_e32 v20, 0x3377d1cf, v11
	v_fmac_f32_e32 v20, 0x3f317217, v11
	v_cmp_lt_f32_e64 s[6:7], |v11|, s90
	s_nop 1
	v_cndmask_b32_e64 v11, v11, v20, s[6:7]
	v_cndmask_b32_e64 v20, 0, v238, s[4:5]
	v_sub_f32_e32 v20, v11, v20
	v_mul_f32_e64 v11, |v17|, s20
	v_exp_f32_e32 v11, v11
	s_nop 0
	v_add_f32_e32 v11, 1.0, v11
	v_cmp_gt_f32_e64 s[4:5], s33, v11
	s_nop 1
	v_cndmask_b32_e64 v17, 0, 32, s[4:5]
	v_ldexp_f32 v11, v11, v17
	v_log_f32_e32 v11, v11
	s_nop 0
	v_mul_f32_e32 v17, 0x3f317217, v11
	v_fma_f32 v17, v11, s92, -v17
	v_fmac_f32_e32 v17, 0x3377d1cf, v11
	v_fmac_f32_e32 v17, 0x3f317217, v11
	v_cmp_lt_f32_e64 s[6:7], |v11|, s90
	s_nop 1
	v_cndmask_b32_e64 v11, v11, v17, s[6:7]
	v_cndmask_b32_e64 v17, 0, v238, s[4:5]
	v_sub_f32_e32 v17, v11, v17
	v_mul_f32_e64 v11, |v21|, s20
	v_exp_f32_e32 v11, v11
	v_pk_add_f32 v[16:17], v[26:27], v[16:17] neg_lo:[0,1] neg_hi:[0,1]
	v_add_f32_e32 v11, 1.0, v11
	v_cmp_gt_f32_e64 s[4:5], s33, v11
	v_pk_mul_f32 v[16:17], v[16:17], s[0:1] op_sel_hi:[1,0]
	s_nop 0
	v_cndmask_b32_e64 v21, 0, 32, s[4:5]
	v_ldexp_f32 v11, v11, v21
	v_log_f32_e32 v11, v11
	s_nop 0
	v_mul_f32_e32 v21, 0x3f317217, v11
	v_fma_f32 v21, v11, s92, -v21
	v_fmac_f32_e32 v21, 0x3377d1cf, v11
	v_fmac_f32_e32 v21, 0x3f317217, v11
	v_cmp_lt_f32_e64 s[6:7], |v11|, s90
	s_nop 1
	v_cndmask_b32_e64 v11, v11, v21, s[6:7]
	v_cndmask_b32_e64 v21, 0, v238, s[4:5]
	s_movk_i32 s6, 0x110
	v_sub_f32_e32 v21, v11, v21
	v_mul_lo_u32 v11, v8, s6
	v_add_u32_e32 v11, 0, v11
	v_pk_add_f32 v[20:21], v[28:29], v[20:21] neg_lo:[0,1] neg_hi:[0,1]
	v_add_u32_e32 v10, v11, v10
	v_pk_mul_f32 v[20:21], v[20:21], s[0:1] op_sel_hi:[1,0]
	ds_write_b128 v10, v[14:17]
	ds_write_b128 v10, v[18:21] offset:16
	v_lshlrev_b32_e32 v10, 7, v8
	v_sub_u32_e32 v10, v11, v10
	v_add_u32_e32 v10, v10, v112
	ds_write_b128 v10, v[0:3] offset:33792
	v_and_b32_e32 v1, -8, v35
	v_lshlrev_b32_e32 v0, 1, v35
	v_add_u32_e32 v1, 32, v1
	v_and_b32_e32 v0, 14, v0
	v_bitop3_b32 v2, v35, v13, -8 bitop3:0x6c
	v_bitop3_b32 v1, v1, v9, 56 bitop3:0x78
	v_add_u32_e32 v0, s95, v0
	v_lshlrev_b32_e32 v2, 1, v2
	v_mul_u32_u24_e32 v3, 0x90, v37
	v_lshlrev_b32_e32 v1, 1, v1
	v_add3_u32 v2, v0, v2, v3
	v_add3_u32 v0, v0, v1, v3
	s_waitcnt vmcnt(0) lgkmcnt(0)
	ds_write_b16 v2, v22
	ds_write_b16_d16_hi v2, v22 offset:144
	ds_write_b16 v2, v23 offset:288
	ds_write_b16_d16_hi v2, v23 offset:432
	ds_write_b16 v2, v24 offset:576
	ds_write_b16_d16_hi v2, v24 offset:720
	ds_write_b16 v2, v25 offset:864
	ds_write_b16_d16_hi v2, v25 offset:1008
	ds_write_b16 v0, v4
	ds_write_b16_d16_hi v0, v4 offset:144
	ds_write_b16 v0, v5 offset:288
	ds_write_b16_d16_hi v0, v5 offset:432
	ds_write_b16 v0, v6 offset:576
	ds_write_b16_d16_hi v0, v6 offset:720
	ds_write_b16 v0, v7 offset:864
	ds_write_b16_d16_hi v0, v7 offset:1008
	v_ashrrev_i32_e32 v0, 31, v12
	v_lshrrev_b32_e32 v0, 26, v0
	v_add_u32_e32 v0, v12, v0
	v_ashrrev_i32_e32 v1, 6, v0
	v_and_b32_e32 v0, 0x3fffffc0, v0
	v_sub_u32_e32 v0, v12, v0
	v_lshlrev_b32_e32 v4, 3, v1
	v_lshlrev_b32_e32 v5, 2, v0
	v_add_u32_e32 v0, 0, v5
	v_and_or_b32 v2, s18, 7, v4
	v_mad_u64_u32 v[2:3], s[4:5], v2, s6, v[0:1]
	s_waitcnt lgkmcnt(0)
	s_barrier
; template <int TYPE>
; __device__ __forceinline__ void cumsum_g(int dir, LAS unsigned char* lds, int tid) {
;     ...
;     const int d = tid % C::DK, seg = tid / C::DK;
;     __syncthreads();
;     float run = 0.f;
; #pragma unroll
;     for (int ii = 0; ii < SEGL; ++ii) { const int i = seg * SEGL + (dir ? SEGL - 1 - ii : ii); run += G[i * C::LDG + d]; G[i * C::LDG + d] = run; }
;     SG[seg * 128 + d] = run;
;     __syncthreads();
;     float off = 0.f;
; #pragma unroll
;     for (int s = 0; s < NSEG; ++s) { const bool before = dir ? (s > seg) : (s < seg); if (before) off += SG[s * 128 + d]; }
	ds_read_b32 v3, v2
	s_cselect_b32 s4, 1, 6
	s_movk_i32 s0, 0xffc1
	s_waitcnt lgkmcnt(0)
	v_add_f32_e32 v6, 0, v3
	ds_write_b32 v2, v6
	v_or_b32_e32 v2, s4, v4
	v_mad_u64_u32 v[2:3], s[4:5], v2, s6, v[0:1]
	ds_read_b32 v3, v2
	s_cselect_b32 s4, 2, 5
	s_waitcnt lgkmcnt(0)
	v_add_f32_e32 v6, v6, v3
	ds_write_b32 v2, v6
	v_or_b32_e32 v2, s4, v4
	v_mad_u64_u32 v[2:3], s[4:5], v2, s6, v[0:1]
	ds_read_b32 v3, v2
	s_waitcnt lgkmcnt(0)
	v_add_f32_e32 v6, v6, v3
	ds_write_b32 v2, v6
	v_or_b32_e32 v2, s19, v4
	v_mad_u64_u32 v[2:3], s[4:5], v2, s6, v[0:1]
	ds_read_b32 v3, v2
	s_waitcnt lgkmcnt(0)
	v_add_f32_e32 v6, v6, v3
	ds_write_b32 v2, v6
	v_subrev_u32_e32 v2, s17, v4
	v_mad_u64_u32 v[2:3], s[4:5], v2, s6, v[0:1]
	ds_read_b32 v3, v2 offset:1088
	s_cselect_b32 s4, 5, 2
	s_waitcnt lgkmcnt(0)
	v_add_f32_e32 v6, v6, v3
	ds_write_b32 v2, v6 offset:1088
	v_or_b32_e32 v2, s4, v4
	v_mad_u64_u32 v[2:3], s[4:5], v2, s6, v[0:1]
	ds_read_b32 v3, v2
	s_cselect_b32 s4, 6, 1
	s_waitcnt lgkmcnt(0)
	v_add_f32_e32 v6, v6, v3
	ds_write_b32 v2, v6
	v_or_b32_e32 v2, s4, v4
	v_mad_u64_u32 v[2:3], s[4:5], v2, s6, v[0:1]
	ds_read_b32 v3, v2
	s_cselect_b32 s4, 7, 0
	s_waitcnt lgkmcnt(0)
	v_add_f32_e32 v6, v6, v3
	ds_write_b32 v2, v6
	v_or_b32_e32 v2, s4, v4
	v_mad_u64_u32 v[2:3], s[4:5], v2, s6, v[0:1]
	ds_read_b32 v3, v2
	v_cmp_gt_i32_e64 s[4:5], s0, v12
	v_cmp_lt_i32_e64 s[6:7], 63, v12
	s_waitcnt lgkmcnt(0)
	v_add_f32_e32 v3, v6, v3
	ds_write_b32 v2, v3
	v_add_u32_e32 v2, s74, v5
	v_lshl_add_u32 v4, v1, 9, v2
	ds_write_b32 v4, v3
	v_cndmask_b32_e64 v3, 0, 1, s[6:7]
	v_cndmask_b32_e64 v4, 0, 1, s[4:5]
	v_cndmask_b32_e32 v3, v4, v3, vcc
	v_and_b32_e32 v3, 1, v3
	v_cmp_eq_u32_e64 s[4:5], 1, v3
	v_mov_b32_e32 v3, 0
	s_waitcnt lgkmcnt(0)
	s_barrier
	s_and_saveexec_b64 s[6:7], s[4:5]
	s_cbranch_execz .LBB0_290
	ds_read_b32 v3, v2
	s_waitcnt lgkmcnt(0)
	v_add_f32_e32 v3, 0, v3

; __device__ __forceinline__ float bf2f(unsigned v) { return __uint_as_float(v << 16); }
; template <int TYPE>
; __device__ __forceinline__ void pass3_item(const KArgs& a, int l, int item, LAS unsigned char* lds) {
;     ...
;     const float gain = ((const float*)a.in[TYPE ? 7 : 5])[l * 128 + wid * 16 + fr];
;     bf16_t* mix = (bf16_t*)(wsb + WS_XN);
;     float gtv[4][4];
; #pragma unroll
;     for (int it = 0; it < 4; ++it)
; #pragma unroll
;         for (int r = 0; r < 4; ++r) gtv[it][r] = bf2f(u[(tok0 + it * 16 + fq * 4 + r) * DINP + (TYPE ? C_HG : C_GG) + h * 128 + wid * 16 + fr]);
.LBB0_492:
	s_or_b64 exec, exec, s[6:7]
	v_readlane_b32 s6, v255, 29
	v_readlane_b32 s8, v253, 48
	v_readlane_b32 s22, v253, 62
	v_add_u32_e32 v16, s6, v64
	v_or_b32_e32 v16, v16, v89
	v_ashrrev_i32_e32 v17, 31, v16
	v_readlane_b32 s23, v253, 63
	v_readlane_b32 s9, v253, 49
	v_or_b32_e32 v42, s60, v83
	v_lshl_add_u64 v[16:17], v[16:17], 2, s[22:23]
	v_mov_b64_e32 v[50:51], s[62:63]
	s_movk_i32 s2, 0x2a00
	s_waitcnt lgkmcnt(0)
	s_barrier
	global_load_dword v52, v[16:17], off
	s_mul_i32 s6, s61, 0x2a00
	v_mad_u64_u32 v[16:17], s[8:9], v42, s2, v[50:51]
	v_ashrrev_i32_e32 v65, 31, v64
	v_add_u32_e32 v17, s6, v17
	s_lshl_b32 s72, s5, 1
	v_lshl_add_u64 v[16:17], v[16:17], 0, s[72:73]
	v_lshlrev_b64 v[24:25], 1, v[64:65]
	v_lshl_add_u64 v[16:17], v[16:17], 0, v[24:25]
	v_lshlrev_b32_e32 v112, 1, v89
	v_lshl_add_u64 v[16:17], v[16:17], 0, v[112:113]
	s_movk_i32 s77, 0x1000
	v_add_co_u32_e32 v16, vcc, s77, v16
	v_or_b32_e32 v44, 1, v42
	s_nop 0
	v_addc_co_u32_e32 v17, vcc, 0, v17, vcc
	global_load_ushort v142, v[16:17], off offset:3136
	v_or_b32_e32 v46, 2, v42
	v_or_b32_e32 v48, 3, v42
	v_or_b32_e32 v66, 16, v83
	v_or_b32_e32 v40, s60, v66
	v_or_b32_e32 v38, 17, v42
	v_or_b32_e32 v34, 18, v42
	v_or_b32_e32 v28, 19, v42
	v_or_b32_e32 v59, 32, v83
	v_or_b32_e32 v26, s60, v59
	v_or_b32_e32 v30, 33, v42
	v_or_b32_e32 v32, 34, v42
	v_or_b32_e32 v36, 35, v42
	v_or_b32_e32 v56, 48, v83
	v_or_b32_e32 v22, s60, v56
	v_or_b32_e32 v20, 49, v42
	v_or_b32_e32 v18, 50, v42
	v_mov_b32_e32 v43, s61
	v_mov_b32_e32 v45, s61
	v_mov_b32_e32 v47, s61
	v_mov_b32_e32 v49, s61
	v_mov_b32_e32 v41, s61
	v_mov_b32_e32 v39, s61
	v_mov_b32_e32 v35, s61
	v_mov_b32_e32 v29, s61
	v_mov_b32_e32 v27, s61
	v_mov_b32_e32 v31, s61
	v_mov_b32_e32 v33, s61
	v_mov_b32_e32 v37, s61
	v_mov_b32_e32 v23, s61
	v_mov_b32_e32 v21, s61
	v_mov_b32_e32 v19, s61
	v_readlane_b32 s68, v255, 16
	v_readlane_b32 s70, v255, 18
	v_readlane_b32 s69, v255, 17
	s_movk_i32 s66, 0x80
	s_movk_i32 s67, 0x100
	s_movk_i32 s3, 0x90
	v_readlane_b32 s10, v253, 50
	v_readlane_b32 s11, v253, 51
	v_readlane_b32 s12, v253, 52
	v_readlane_b32 s13, v253, 53
	v_readlane_b32 s14, v253, 54
	v_readlane_b32 s15, v253, 55
	v_readlane_b32 s16, v253, 56
	v_readlane_b32 s17, v253, 57
	v_readlane_b32 s18, v253, 58
	v_readlane_b32 s19, v253, 59
	v_readlane_b32 s20, v253, 60
	v_readlane_b32 s21, v253, 61
	v_readlane_b32 s71, v255, 19


; __device__ __forceinline__ float bf2f(unsigned v) { return __uint_as_float(v << 16); }
; template <int TYPE>
; __device__ __forceinline__ void pass3_item(const KArgs& a, int l, int item, LAS unsigned char* lds) {
;     ...
;     const float gain = ((const float*)a.in[TYPE ? 7 : 5])[l * 128 + wid * 16 + fr];
;     bf16_t* mix = (bf16_t*)(wsb + WS_XN);
;     float gtv[4][4];
; #pragma unroll
;     for (int it = 0; it < 4; ++it)
; #pragma unroll
;         for (int r = 0; r < 4; ++r) gtv[it][r] = bf2f(u[(tok0 + it * 16 + fq * 4 + r) * DINP + (TYPE ? C_HG : C_GG) + h * 128 + wid * 16 + fr]);
	v_mad_u64_u32 v[16:17], s[8:9], v44, s2, v[50:51]
	v_add_u32_e32 v17, s6, v17
	v_lshl_add_u64 v[16:17], v[16:17], 0, s[72:73]
	v_lshl_add_u64 v[16:17], v[16:17], 0, v[24:25]
	v_lshl_add_u64 v[16:17], v[16:17], 0, v[112:113]
	v_add_co_u32_e32 v16, vcc, s77, v16
	s_nop 1
	v_addc_co_u32_e32 v17, vcc, 0, v17, vcc
	global_load_ushort v143, v[16:17], off offset:3136


; __device__ __forceinline__ float bf2f(unsigned v) { return __uint_as_float(v << 16); }
; template <int TYPE>
; __device__ __forceinline__ void pass3_item(const KArgs& a, int l, int item, LAS unsigned char* lds) {
;     ...
;     const float gain = ((const float*)a.in[TYPE ? 7 : 5])[l * 128 + wid * 16 + fr];
;     bf16_t* mix = (bf16_t*)(wsb + WS_XN);
;     float gtv[4][4];
; #pragma unroll
;     for (int it = 0; it < 4; ++it)
; #pragma unroll
;         for (int r = 0; r < 4; ++r) gtv[it][r] = bf2f(u[(tok0 + it * 16 + fq * 4 + r) * DINP + (TYPE ? C_HG : C_GG) + h * 128 + wid * 16 + fr]);
	v_mad_u64_u32 v[16:17], s[8:9], v46, s2, v[50:51]
	v_add_u32_e32 v17, s6, v17
	v_lshl_add_u64 v[16:17], v[16:17], 0, s[72:73]
	v_lshl_add_u64 v[16:17], v[16:17], 0, v[24:25]
	v_lshl_add_u64 v[16:17], v[16:17], 0, v[112:113]
	v_add_co_u32_e32 v16, vcc, s77, v16
	s_nop 1
	v_addc_co_u32_e32 v17, vcc, 0, v17, vcc
	global_load_ushort v144, v[16:17], off offset:3136


; __device__ __forceinline__ float bf2f(unsigned v) { return __uint_as_float(v << 16); }
; template <int TYPE>
; __device__ __forceinline__ void pass3_item(const KArgs& a, int l, int item, LAS unsigned char* lds) {
;     ...
;     const float gain = ((const float*)a.in[TYPE ? 7 : 5])[l * 128 + wid * 16 + fr];
;     bf16_t* mix = (bf16_t*)(wsb + WS_XN);
;     float gtv[4][4];
; #pragma unroll
;     for (int it = 0; it < 4; ++it)
; #pragma unroll
;         for (int r = 0; r < 4; ++r) gtv[it][r] = bf2f(u[(tok0 + it * 16 + fq * 4 + r) * DINP + (TYPE ? C_HG : C_GG) + h * 128 + wid * 16 + fr]);
	v_mad_u64_u32 v[16:17], s[8:9], v48, s2, v[50:51]
	v_add_u32_e32 v17, s6, v17
	v_lshl_add_u64 v[16:17], v[16:17], 0, s[72:73]
	v_lshl_add_u64 v[16:17], v[16:17], 0, v[24:25]
	v_lshl_add_u64 v[16:17], v[16:17], 0, v[112:113]
	v_add_co_u32_e32 v16, vcc, s77, v16
	s_nop 1
	v_addc_co_u32_e32 v17, vcc, 0, v17, vcc
	global_load_ushort v145, v[16:17], off offset:3136


; __device__ __forceinline__ float bf2f(unsigned v) { return __uint_as_float(v << 16); }
; template <int TYPE>
; __device__ __forceinline__ void pass3_item(const KArgs& a, int l, int item, LAS unsigned char* lds) {
;     ...
;     const float gain = ((const float*)a.in[TYPE ? 7 : 5])[l * 128 + wid * 16 + fr];
;     bf16_t* mix = (bf16_t*)(wsb + WS_XN);
;     float gtv[4][4];
; #pragma unroll
;     for (int it = 0; it < 4; ++it)
; #pragma unroll
;         for (int r = 0; r < 4; ++r) gtv[it][r] = bf2f(u[(tok0 + it * 16 + fq * 4 + r) * DINP + (TYPE ? C_HG : C_GG) + h * 128 + wid * 16 + fr]);
	v_mad_u64_u32 v[16:17], s[8:9], v40, s2, v[50:51]
	v_add_u32_e32 v17, s6, v17
	v_lshl_add_u64 v[16:17], v[16:17], 0, s[72:73]
	v_lshl_add_u64 v[16:17], v[16:17], 0, v[24:25]
	v_lshl_add_u64 v[16:17], v[16:17], 0, v[112:113]
	v_add_co_u32_e32 v16, vcc, s77, v16
	v_lshlrev_b64 v[40:41], 12, v[40:41]
	s_nop 0
	v_addc_co_u32_e32 v17, vcc, 0, v17, vcc
	global_load_ushort v146, v[16:17], off offset:3136


; __device__ __forceinline__ float bf2f(unsigned v) { return __uint_as_float(v << 16); }
; template <int TYPE>
; __device__ __forceinline__ void pass3_item(const KArgs& a, int l, int item, LAS unsigned char* lds) {
;     ...
;     const float gain = ((const float*)a.in[TYPE ? 7 : 5])[l * 128 + wid * 16 + fr];
;     bf16_t* mix = (bf16_t*)(wsb + WS_XN);
;     float gtv[4][4];
; #pragma unroll
;     for (int it = 0; it < 4; ++it)
; #pragma unroll
;         for (int r = 0; r < 4; ++r) gtv[it][r] = bf2f(u[(tok0 + it * 16 + fq * 4 + r) * DINP + (TYPE ? C_HG : C_GG) + h * 128 + wid * 16 + fr]);
	v_mad_u64_u32 v[16:17], s[8:9], v38, s2, v[50:51]
	v_add_u32_e32 v17, s6, v17
	v_lshl_add_u64 v[16:17], v[16:17], 0, s[72:73]
	v_lshl_add_u64 v[16:17], v[16:17], 0, v[24:25]
	v_lshl_add_u64 v[16:17], v[16:17], 0, v[112:113]
	v_add_co_u32_e32 v16, vcc, s77, v16
	s_nop 1
	v_addc_co_u32_e32 v17, vcc, 0, v17, vcc
	global_load_ushort v147, v[16:17], off offset:3136


; __device__ __forceinline__ float bf2f(unsigned v) { return __uint_as_float(v << 16); }
; template <int TYPE>
; __device__ __forceinline__ void pass3_item(const KArgs& a, int l, int item, LAS unsigned char* lds) {
;     ...
;     const float gain = ((const float*)a.in[TYPE ? 7 : 5])[l * 128 + wid * 16 + fr];
;     bf16_t* mix = (bf16_t*)(wsb + WS_XN);
;     float gtv[4][4];
; #pragma unroll
;     for (int it = 0; it < 4; ++it)
; #pragma unroll
;         for (int r = 0; r < 4; ++r) gtv[it][r] = bf2f(u[(tok0 + it * 16 + fq * 4 + r) * DINP + (TYPE ? C_HG : C_GG) + h * 128 + wid * 16 + fr]);
	v_mad_u64_u32 v[16:17], s[8:9], v34, s2, v[50:51]
	v_add_u32_e32 v17, s6, v17
	v_lshl_add_u64 v[16:17], v[16:17], 0, s[72:73]
	v_lshl_add_u64 v[16:17], v[16:17], 0, v[24:25]
	v_lshl_add_u64 v[16:17], v[16:17], 0, v[112:113]
	v_add_co_u32_e32 v16, vcc, s77, v16
	s_nop 1
	v_addc_co_u32_e32 v17, vcc, 0, v17, vcc
	global_load_ushort v148, v[16:17], off offset:3136


; __device__ __forceinline__ float bf2f(unsigned v) { return __uint_as_float(v << 16); }
; template <int TYPE>
; __device__ __forceinline__ void pass3_item(const KArgs& a, int l, int item, LAS unsigned char* lds) {
;     ...
;     const float gain = ((const float*)a.in[TYPE ? 7 : 5])[l * 128 + wid * 16 + fr];
;     bf16_t* mix = (bf16_t*)(wsb + WS_XN);
;     float gtv[4][4];
; #pragma unroll
;     for (int it = 0; it < 4; ++it)
; #pragma unroll
;         for (int r = 0; r < 4; ++r) gtv[it][r] = bf2f(u[(tok0 + it * 16 + fq * 4 + r) * DINP + (TYPE ? C_HG : C_GG) + h * 128 + wid * 16 + fr]);
	v_mad_u64_u32 v[16:17], s[8:9], v28, s2, v[50:51]
	v_add_u32_e32 v17, s6, v17
	v_lshl_add_u64 v[16:17], v[16:17], 0, s[72:73]
	v_lshl_add_u64 v[16:17], v[16:17], 0, v[24:25]
	v_lshl_add_u64 v[16:17], v[16:17], 0, v[112:113]
	v_add_co_u32_e32 v16, vcc, s77, v16
	s_nop 1
	v_addc_co_u32_e32 v17, vcc, 0, v17, vcc
	global_load_ushort v149, v[16:17], off offset:3136


; __device__ __forceinline__ float bf2f(unsigned v) { return __uint_as_float(v << 16); }
; template <int TYPE>
; __device__ __forceinline__ void pass3_item(const KArgs& a, int l, int item, LAS unsigned char* lds) {
;     ...
;     const float gain = ((const float*)a.in[TYPE ? 7 : 5])[l * 128 + wid * 16 + fr];
;     bf16_t* mix = (bf16_t*)(wsb + WS_XN);
;     float gtv[4][4];
; #pragma unroll
;     for (int it = 0; it < 4; ++it)
; #pragma unroll
;         for (int r = 0; r < 4; ++r) gtv[it][r] = bf2f(u[(tok0 + it * 16 + fq * 4 + r) * DINP + (TYPE ? C_HG : C_GG) + h * 128 + wid * 16 + fr]);
	v_mad_u64_u32 v[16:17], s[8:9], v26, s2, v[50:51]
	v_add_u32_e32 v17, s6, v17
	v_lshl_add_u64 v[16:17], v[16:17], 0, s[72:73]
	v_lshl_add_u64 v[16:17], v[16:17], 0, v[24:25]
	v_lshl_add_u64 v[16:17], v[16:17], 0, v[112:113]
	v_add_co_u32_e32 v16, vcc, s77, v16
	s_nop 1
	v_addc_co_u32_e32 v17, vcc, 0, v17, vcc
	global_load_ushort v150, v[16:17], off offset:3136


; __device__ __forceinline__ float bf2f(unsigned v) { return __uint_as_float(v << 16); }
; template <int TYPE>
; __device__ __forceinline__ void pass3_item(const KArgs& a, int l, int item, LAS unsigned char* lds) {
;     ...
;     const float gain = ((const float*)a.in[TYPE ? 7 : 5])[l * 128 + wid * 16 + fr];
;     bf16_t* mix = (bf16_t*)(wsb + WS_XN);
;     float gtv[4][4];
; #pragma unroll
;     for (int it = 0; it < 4; ++it)
; #pragma unroll
;         for (int r = 0; r < 4; ++r) gtv[it][r] = bf2f(u[(tok0 + it * 16 + fq * 4 + r) * DINP + (TYPE ? C_HG : C_GG) + h * 128 + wid * 16 + fr]);
	v_mad_u64_u32 v[16:17], s[8:9], v30, s2, v[50:51]
	v_add_u32_e32 v17, s6, v17
	v_lshl_add_u64 v[16:17], v[16:17], 0, s[72:73]
	v_lshl_add_u64 v[16:17], v[16:17], 0, v[24:25]
	v_lshl_add_u64 v[16:17], v[16:17], 0, v[112:113]
	v_add_co_u32_e32 v16, vcc, s77, v16
	s_nop 1
	v_addc_co_u32_e32 v17, vcc, 0, v17, vcc
	global_load_ushort v151, v[16:17], off offset:3136


; __device__ __forceinline__ float bf2f(unsigned v) { return __uint_as_float(v << 16); }
; template <int TYPE>
; __device__ __forceinline__ void pass3_item(const KArgs& a, int l, int item, LAS unsigned char* lds) {
;     ...
;     const float gain = ((const float*)a.in[TYPE ? 7 : 5])[l * 128 + wid * 16 + fr];
;     bf16_t* mix = (bf16_t*)(wsb + WS_XN);
;     float gtv[4][4];
; #pragma unroll
;     for (int it = 0; it < 4; ++it)
; #pragma unroll
;         for (int r = 0; r < 4; ++r) gtv[it][r] = bf2f(u[(tok0 + it * 16 + fq * 4 + r) * DINP + (TYPE ? C_HG : C_GG) + h * 128 + wid * 16 + fr]);
	v_mad_u64_u32 v[16:17], s[8:9], v32, s2, v[50:51]
	v_add_u32_e32 v17, s6, v17
	v_lshl_add_u64 v[16:17], v[16:17], 0, s[72:73]
	v_lshl_add_u64 v[16:17], v[16:17], 0, v[24:25]
	v_lshl_add_u64 v[16:17], v[16:17], 0, v[112:113]
	v_add_co_u32_e32 v16, vcc, s77, v16
	s_nop 1
	v_addc_co_u32_e32 v17, vcc, 0, v17, vcc
	global_load_ushort v152, v[16:17], off offset:3136


; __device__ __forceinline__ float bf2f(unsigned v) { return __uint_as_float(v << 16); }
; template <int TYPE>
; __device__ __forceinline__ void pass3_item(const KArgs& a, int l, int item, LAS unsigned char* lds) {
;     ...
;     const float gain = ((const float*)a.in[TYPE ? 7 : 5])[l * 128 + wid * 16 + fr];
;     bf16_t* mix = (bf16_t*)(wsb + WS_XN);
;     float gtv[4][4];
; #pragma unroll
;     for (int it = 0; it < 4; ++it)
; #pragma unroll
;         for (int r = 0; r < 4; ++r) gtv[it][r] = bf2f(u[(tok0 + it * 16 + fq * 4 + r) * DINP + (TYPE ? C_HG : C_GG) + h * 128 + wid * 16 + fr]);
	v_mad_u64_u32 v[16:17], s[8:9], v36, s2, v[50:51]
	v_add_u32_e32 v17, s6, v17
	v_lshl_add_u64 v[16:17], v[16:17], 0, s[72:73]
	v_lshl_add_u64 v[16:17], v[16:17], 0, v[24:25]
	v_lshl_add_u64 v[16:17], v[16:17], 0, v[112:113]
	v_add_co_u32_e32 v16, vcc, s77, v16
	s_nop 1
	v_addc_co_u32_e32 v17, vcc, 0, v17, vcc
	global_load_ushort v153, v[16:17], off offset:3136


; __device__ __forceinline__ float bf2f(unsigned v) { return __uint_as_float(v << 16); }
; template <int TYPE>
; __device__ __forceinline__ void pass3_item(const KArgs& a, int l, int item, LAS unsigned char* lds) {
;     ...
;     const float gain = ((const float*)a.in[TYPE ? 7 : 5])[l * 128 + wid * 16 + fr];
;     bf16_t* mix = (bf16_t*)(wsb + WS_XN);
;     float gtv[4][4];
; #pragma unroll
;     for (int it = 0; it < 4; ++it)
; #pragma unroll
;         for (int r = 0; r < 4; ++r) gtv[it][r] = bf2f(u[(tok0 + it * 16 + fq * 4 + r) * DINP + (TYPE ? C_HG : C_GG) + h * 128 + wid * 16 + fr]);
	v_mad_u64_u32 v[16:17], s[8:9], v22, s2, v[50:51]
	v_add_u32_e32 v17, s6, v17
	v_lshl_add_u64 v[16:17], v[16:17], 0, s[72:73]
	v_lshl_add_u64 v[16:17], v[16:17], 0, v[24:25]
	v_lshl_add_u64 v[16:17], v[16:17], 0, v[112:113]
	v_add_co_u32_e32 v16, vcc, s77, v16
	s_nop 1
	v_addc_co_u32_e32 v17, vcc, 0, v17, vcc
	global_load_ushort v154, v[16:17], off offset:3136


; __device__ __forceinline__ float bf2f(unsigned v) { return __uint_as_float(v << 16); }
; template <int TYPE>
; __device__ __forceinline__ void pass3_item(const KArgs& a, int l, int item, LAS unsigned char* lds) {
;     ...
;     const float gain = ((const float*)a.in[TYPE ? 7 : 5])[l * 128 + wid * 16 + fr];
;     bf16_t* mix = (bf16_t*)(wsb + WS_XN);
;     float gtv[4][4];
; #pragma unroll
;     for (int it = 0; it < 4; ++it)
; #pragma unroll
;         for (int r = 0; r < 4; ++r) gtv[it][r] = bf2f(u[(tok0 + it * 16 + fq * 4 + r) * DINP + (TYPE ? C_HG : C_GG) + h * 128 + wid * 16 + fr]);
	v_mad_u64_u32 v[16:17], s[8:9], v20, s2, v[50:51]
	v_add_u32_e32 v17, s6, v17
	v_lshl_add_u64 v[16:17], v[16:17], 0, s[72:73]
	v_lshl_add_u64 v[16:17], v[16:17], 0, v[24:25]
	v_lshl_add_u64 v[16:17], v[16:17], 0, v[112:113]
	v_add_co_u32_e32 v16, vcc, s77, v16
	s_nop 1
	v_addc_co_u32_e32 v17, vcc, 0, v17, vcc
	global_load_ushort v155, v[16:17], off offset:3136


; __device__ __forceinline__ float bf2f(unsigned v) { return __uint_as_float(v << 16); }
; template <int TYPE>
; __device__ __forceinline__ void pass3_item(const KArgs& a, int l, int item, LAS unsigned char* lds) {
;     ...
;     const float gain = ((const float*)a.in[TYPE ? 7 : 5])[l * 128 + wid * 16 + fr];
;     bf16_t* mix = (bf16_t*)(wsb + WS_XN);
;     float gtv[4][4];
; #pragma unroll
;     for (int it = 0; it < 4; ++it)
; #pragma unroll
;         for (int r = 0; r < 4; ++r) gtv[it][r] = bf2f(u[(tok0 + it * 16 + fq * 4 + r) * DINP + (TYPE ? C_HG : C_GG) + h * 128 + wid * 16 + fr]);
	v_mad_u64_u32 v[16:17], s[8:9], v18, s2, v[50:51]
	v_add_u32_e32 v17, s6, v17
	v_lshl_add_u64 v[16:17], v[16:17], 0, s[72:73]
	v_lshl_add_u64 v[16:17], v[16:17], 0, v[24:25]
	v_lshl_add_u64 v[16:17], v[16:17], 0, v[112:113]
	v_add_co_u32_e32 v16, vcc, s77, v16
	s_nop 1
	v_addc_co_u32_e32 v17, vcc, 0, v17, vcc
	global_load_ushort v156, v[16:17], off offset:3136
	v_mov_b32_e32 v17, s61

; __device__ __forceinline__ float bf2f(unsigned v) { return __uint_as_float(v << 16); }
; __device__ __forceinline__ unsigned f2bf(float f) { unsigned u = __float_as_uint(f); return (u + 0x7fffu + ((u >> 16) & 1u)) >> 16; }
; __device__ __forceinline__ float silu_(float z) { return z * sigmoid_(z); }
; template <int TYPE>
; __device__ __forceinline__ void pass3_item(const KArgs& a, int l, int item, LAS unsigned char* lds) {
;     ...
;     const float gain = ((const float*)a.in[TYPE ? 7 : 5])[l * 128 + wid * 16 + fr];
;     bf16_t* mix = (bf16_t*)(wsb + WS_XN);
;     float gtv[4][4];
; #pragma unroll
;     for (int it = 0; it < 4; ++it)
; #pragma unroll
;         for (int r = 0; r < 4; ++r) gtv[it][r] = bf2f(u[(tok0 + it * 16 + fq * 4 + r) * DINP + (TYPE ? C_HG : C_GG) + h * 128 + wid * 16 + fr]);
; #pragma unroll
;     for (int it = 0; it < 4; ++it)
; #pragma unroll
;         for (int r = 0; r < 4; ++r) { const int i = it * 16 + fq * 4 + r;
;             const float rstd = RSTD[i];
;             const float gt = gtv[it][r];
;             const float yv = o[it][r] * rstd * gain * silu_(gt);
;             mix[(tok0 + i) * DM + (TYPE ? 512 : 0) + h * 128 + wid * 16 + fr] = (bf16_t)f2bf(yv); }
	s_waitcnt vmcnt(0) lgkmcnt(0)
	v_lshlrev_b32_e32 v67, 16, v142
	v_lshlrev_b32_e32 v68, 16, v143
	v_lshlrev_b32_e32 v69, 16, v144
	v_lshlrev_b32_e32 v70, 16, v145
	v_lshlrev_b32_e32 v65, 16, v146
	v_lshlrev_b32_e32 v64, 16, v147
	v_lshlrev_b32_e32 v62, 16, v148
	v_lshlrev_b32_e32 v60, 16, v149
	v_lshlrev_b32_e32 v57, 16, v150
	v_lshlrev_b32_e32 v58, 16, v151
	v_lshlrev_b32_e32 v61, 16, v152
	v_lshlrev_b32_e32 v63, 16, v153
	v_lshlrev_b32_e32 v55, 16, v154
	v_lshlrev_b32_e32 v54, 16, v155
	v_lshlrev_b32_e32 v53, 16, v156
	v_or_b32_e32 v16, 51, v42
	v_mad_u64_u32 v[50:51], s[8:9], v16, s2, v[50:51]
	v_add_u32_e32 v51, s6, v51
	v_lshl_add_u64 v[50:51], v[50:51], 0, s[72:73]
	v_lshl_add_u64 v[50:51], v[50:51], 0, v[24:25]
	v_lshl_add_u64 v[50:51], v[50:51], 0, v[112:113]
	v_add_co_u32_e32 v50, vcc, s77, v50
	s_add_u32 s6, s58, s72
	s_nop 0
	v_addc_co_u32_e32 v51, vcc, 0, v51, vcc
	global_load_ushort v50, v[50:51], off offset:3136
	v_lshl_add_u32 v51, v83, 2, s74
	ds_read_b128 v[72:75], v51
	v_mul_f32_e32 v51, 0xbfb8aa3b, v67
	v_exp_f32_e32 v51, v51
	s_addc_u32 s7, s59, 0
	v_lshl_add_u64 v[24:25], s[6:7], 0, v[24:25]
	s_waitcnt lgkmcnt(0)
	v_mul_f32_e32 v12, v12, v72
	v_add_f32_e32 v51, 1.0, v51
	v_rcp_f32_e32 v51, v51
	v_mul_f32_e32 v12, v52, v12
	v_lshl_add_u64 v[24:25], v[24:25], 0, v[112:113]
	s_mov_b64 s[6:7], 0x6300400
	v_mul_f32_e32 v51, v51, v67
	v_mul_f32_e32 v12, v51, v12
	v_lshl_add_u64 v[24:25], v[24:25], 0, s[6:7]
	v_bfe_u32 v51, v12, 16, 1
	v_lshlrev_b64 v[42:43], 12, v[42:43]
	v_add3_u32 v12, v12, v51, s1
	v_lshl_add_u64 v[42:43], v[24:25], 0, v[42:43]
	global_store_short_d16_hi v[42:43], v12, off
	v_mul_f32_e32 v12, v13, v73
	v_mul_f32_e32 v13, 0xbfb8aa3b, v68
	v_exp_f32_e32 v13, v13
	v_mul_f32_e32 v12, v52, v12
	v_lshl_add_u64 v[40:41], v[24:25], 0, v[40:41]
	s_add_i32 s4, s4, s70
	v_add_f32_e32 v13, 1.0, v13
	v_rcp_f32_e32 v13, v13
	s_cmpk_gt_i32 s4, 0x7ff
	v_mul_f32_e32 v13, v13, v68
	v_mul_f32_e32 v12, v13, v12
	v_bfe_u32 v13, v12, 16, 1
	v_add3_u32 v42, v12, v13, s1
	v_lshlrev_b64 v[12:13], 12, v[44:45]
	v_lshl_add_u64 v[12:13], v[24:25], 0, v[12:13]
	global_store_short_d16_hi v[12:13], v42, off
	v_mul_f32_e32 v13, 0xbfb8aa3b, v69
	v_exp_f32_e32 v13, v13
	v_mul_f32_e32 v12, v14, v74
	v_mul_f32_e32 v12, v52, v12
	v_add_f32_e32 v13, 1.0, v13
	v_rcp_f32_e32 v13, v13
	s_waitcnt vmcnt(0)
	v_lshlrev_b32_e32 v50, 16, v50
	v_mul_f32_e32 v13, v13, v69
	v_mul_f32_e32 v12, v13, v12
	v_bfe_u32 v13, v12, 16, 1
	v_add3_u32 v14, v12, v13, s1
	v_lshlrev_b64 v[12:13], 12, v[46:47]
	v_lshl_add_u64 v[12:13], v[24:25], 0, v[12:13]
	global_store_short_d16_hi v[12:13], v14, off
	v_mul_f32_e32 v13, 0xbfb8aa3b, v70
	v_exp_f32_e32 v13, v13
	v_mul_f32_e32 v12, v15, v75
	v_mul_f32_e32 v12, v52, v12
	v_add_f32_e32 v13, 1.0, v13
	v_rcp_f32_e32 v13, v13
	s_nop 0
	v_mul_f32_e32 v13, v13, v70
	v_mul_f32_e32 v12, v13, v12
	v_bfe_u32 v13, v12, 16, 1
	v_add3_u32 v14, v12, v13, s1
	v_lshlrev_b64 v[12:13], 12, v[48:49]
	v_lshl_add_u64 v[12:13], v[24:25], 0, v[12:13]
	global_store_short_d16_hi v[12:13], v14, off
	v_lshl_add_u32 v12, v66, 2, s74
	ds_read_b128 v[12:15], v12
	s_waitcnt lgkmcnt(0)
	v_mul_f32_e32 v8, v8, v12
	v_mul_f32_e32 v12, 0xbfb8aa3b, v65
	v_exp_f32_e32 v12, v12
	v_mul_f32_e32 v8, v52, v8
	v_add_f32_e32 v12, 1.0, v12
	v_rcp_f32_e32 v12, v12
	s_nop 0
	v_mul_f32_e32 v12, v12, v65
	v_mul_f32_e32 v8, v12, v8
	v_bfe_u32 v12, v8, 16, 1
	v_add3_u32 v8, v8, v12, s1
	global_store_short_d16_hi v[40:41], v8, off
	v_mul_f32_e32 v8, v9, v13
	v_mul_f32_e32 v9, 0xbfb8aa3b, v64
	v_exp_f32_e32 v9, v9
	v_mul_f32_e32 v8, v52, v8
	v_add_f32_e32 v9, 1.0, v9
	v_rcp_f32_e32 v9, v9
	s_nop 0
	v_mul_f32_e32 v9, v9, v64
	v_mul_f32_e32 v8, v9, v8
	v_bfe_u32 v9, v8, 16, 1
	v_add3_u32 v12, v8, v9, s1
	v_lshlrev_b64 v[8:9], 12, v[38:39]
	v_lshl_add_u64 v[8:9], v[24:25], 0, v[8:9]
	global_store_short_d16_hi v[8:9], v12, off
	v_mul_f32_e32 v9, 0xbfb8aa3b, v62
	v_exp_f32_e32 v9, v9
	v_mul_f32_e32 v8, v10, v14
	v_mul_f32_e32 v8, v52, v8
	v_lshlrev_b64 v[12:13], 12, v[26:27]
	v_add_f32_e32 v9, 1.0, v9
	v_rcp_f32_e32 v9, v9
	v_lshl_add_u64 v[12:13], v[24:25], 0, v[12:13]
	v_mul_f32_e32 v9, v9, v62
	v_mul_f32_e32 v8, v9, v8
	v_bfe_u32 v9, v8, 16, 1
	v_add3_u32 v10, v8, v9, s1
	v_lshlrev_b64 v[8:9], 12, v[34:35]
	v_lshl_add_u64 v[8:9], v[24:25], 0, v[8:9]
	global_store_short_d16_hi v[8:9], v10, off
	v_mul_f32_e32 v9, 0xbfb8aa3b, v60
	v_exp_f32_e32 v9, v9
	v_mul_f32_e32 v8, v11, v15
	v_mul_f32_e32 v8, v52, v8
	v_add_f32_e32 v9, 1.0, v9
	v_rcp_f32_e32 v9, v9
	s_nop 0
	v_mul_f32_e32 v9, v9, v60
	v_mul_f32_e32 v8, v9, v8
	v_bfe_u32 v9, v8, 16, 1
	v_add3_u32 v10, v8, v9, s1
	v_lshlrev_b64 v[8:9], 12, v[28:29]
	v_lshl_add_u64 v[8:9], v[24:25], 0, v[8:9]
	global_store_short_d16_hi v[8:9], v10, off
	v_lshl_add_u32 v8, v59, 2, s74
	ds_read_b128 v[8:11], v8
	s_waitcnt lgkmcnt(0)
; __device__ __forceinline__ unsigned f2bf(float f) { unsigned u = __float_as_uint(f); return (u + 0x7fffu + ((u >> 16) & 1u)) >> 16; }
; __device__ __forceinline__ float silu_(float z) { return z * sigmoid_(z); }
; template <int TYPE>
; __device__ __forceinline__ void pass3_item(const KArgs& a, int l, int item, LAS unsigned char* lds) {
;     ...
;     for (int it = 0; it < 4; ++it)
; #pragma unroll
;         for (int r = 0; r < 4; ++r) { const int i = it * 16 + fq * 4 + r;
;             const float rstd = RSTD[i];
;             const float gt = gtv[it][r];
;             const float yv = o[it][r] * rstd * gain * silu_(gt);
;             mix[(tok0 + i) * DM + (TYPE ? 512 : 0) + h * 128 + wid * 16 + fr] = (bf16_t)f2bf(yv); }
	v_mul_f32_e32 v4, v4, v8
	v_mul_f32_e32 v8, 0xbfb8aa3b, v57
	v_exp_f32_e32 v8, v8
	v_mul_f32_e32 v4, v52, v4
	v_add_f32_e32 v8, 1.0, v8
	v_rcp_f32_e32 v8, v8
	s_nop 0
	v_mul_f32_e32 v8, v8, v57
	v_mul_f32_e32 v4, v8, v4
	v_bfe_u32 v8, v4, 16, 1
	v_add3_u32 v4, v4, v8, s1
	global_store_short_d16_hi v[12:13], v4, off
	v_mul_f32_e32 v4, v5, v9
	v_mul_f32_e32 v5, 0xbfb8aa3b, v58
	v_exp_f32_e32 v5, v5
	v_mul_f32_e32 v4, v52, v4
	v_add_f32_e32 v5, 1.0, v5
	v_rcp_f32_e32 v5, v5
	s_nop 0
	v_mul_f32_e32 v5, v5, v58
	v_mul_f32_e32 v4, v5, v4
	v_bfe_u32 v5, v4, 16, 1
	v_add3_u32 v8, v4, v5, s1
	v_lshlrev_b64 v[4:5], 12, v[30:31]
	v_lshl_add_u64 v[4:5], v[24:25], 0, v[4:5]
	global_store_short_d16_hi v[4:5], v8, off
	v_mul_f32_e32 v5, 0xbfb8aa3b, v61
	v_exp_f32_e32 v5, v5
	v_mul_f32_e32 v4, v6, v10
	v_mul_f32_e32 v4, v52, v4
	v_lshlrev_b64 v[8:9], 12, v[22:23]
	v_add_f32_e32 v5, 1.0, v5
	v_rcp_f32_e32 v5, v5
	v_lshl_add_u64 v[8:9], v[24:25], 0, v[8:9]
	v_mul_f32_e32 v5, v5, v61
	v_mul_f32_e32 v4, v5, v4
	v_bfe_u32 v5, v4, 16, 1
	v_add3_u32 v6, v4, v5, s1
	v_lshlrev_b64 v[4:5], 12, v[32:33]
	v_lshl_add_u64 v[4:5], v[24:25], 0, v[4:5]
	global_store_short_d16_hi v[4:5], v6, off
	v_mul_f32_e32 v5, 0xbfb8aa3b, v63
	v_exp_f32_e32 v5, v5
	v_mul_f32_e32 v4, v7, v11
	v_mul_f32_e32 v4, v52, v4
	v_add_f32_e32 v5, 1.0, v5
	v_rcp_f32_e32 v5, v5
	s_nop 0
	v_mul_f32_e32 v5, v5, v63
	v_mul_f32_e32 v4, v5, v4
	v_bfe_u32 v5, v4, 16, 1
	v_add3_u32 v6, v4, v5, s1
	v_lshlrev_b64 v[4:5], 12, v[36:37]
	v_lshl_add_u64 v[4:5], v[24:25], 0, v[4:5]
	global_store_short_d16_hi v[4:5], v6, off
	v_lshl_add_u32 v4, v56, 2, s74
	ds_read_b128 v[4:7], v4
	s_waitcnt lgkmcnt(0)
	v_mul_f32_e32 v0, v0, v4
	v_mul_f32_e32 v4, 0xbfb8aa3b, v55
	v_exp_f32_e32 v4, v4
	v_mul_f32_e32 v0, v52, v0
	v_add_f32_e32 v4, 1.0, v4
	v_rcp_f32_e32 v4, v4
	s_nop 0
	v_mul_f32_e32 v4, v4, v55
	v_mul_f32_e32 v0, v4, v0
	v_bfe_u32 v4, v0, 16, 1
	v_add3_u32 v0, v0, v4, s1
	global_store_short_d16_hi v[8:9], v0, off
	v_mul_f32_e32 v0, v1, v5
	v_mul_f32_e32 v1, 0xbfb8aa3b, v54
	v_exp_f32_e32 v1, v1
	v_mul_f32_e32 v0, v52, v0
	v_add_f32_e32 v1, 1.0, v1
	v_rcp_f32_e32 v1, v1
	s_nop 0
	v_mul_f32_e32 v1, v1, v54
	v_mul_f32_e32 v0, v1, v0
	v_bfe_u32 v1, v0, 16, 1
	v_add3_u32 v4, v0, v1, s1
	v_lshlrev_b64 v[0:1], 12, v[20:21]
	v_lshl_add_u64 v[0:1], v[24:25], 0, v[0:1]
	global_store_short_d16_hi v[0:1], v4, off
	v_mul_f32_e32 v1, 0xbfb8aa3b, v53
	v_exp_f32_e32 v1, v1
	v_mul_f32_e32 v0, v2, v6
	v_mul_f32_e32 v0, v52, v0
	v_add_f32_e32 v1, 1.0, v1
	v_rcp_f32_e32 v1, v1
	s_nop 0
	v_mul_f32_e32 v1, v1, v53
	v_mul_f32_e32 v0, v1, v0
	v_bfe_u32 v1, v0, 16, 1
	v_add3_u32 v2, v0, v1, s1
	v_lshlrev_b64 v[0:1], 12, v[18:19]
	v_lshl_add_u64 v[0:1], v[24:25], 0, v[0:1]
	global_store_short_d16_hi v[0:1], v2, off
	v_mul_f32_e32 v1, 0xbfb8aa3b, v50
	v_exp_f32_e32 v1, v1
	v_mul_f32_e32 v0, v3, v7
	v_mul_f32_e32 v0, v52, v0
	v_add_f32_e32 v1, 1.0, v1
	v_rcp_f32_e32 v1, v1
	s_nop 0
	v_mul_f32_e32 v1, v1, v50
	v_mul_f32_e32 v0, v1, v0
	v_bfe_u32 v1, v0, 16, 1
	v_add3_u32 v2, v0, v1, s1
	v_lshlrev_b64 v[0:1], 12, v[16:17]
	v_lshl_add_u64 v[0:1], v[24:25], 0, v[0:1]
	global_store_short_d16_hi v[0:1], v2, off
	s_cbranch_scc1 .LBB0_508

; __device__ __forceinline__ float bf2f(unsigned v) { return __uint_as_float(v << 16); }
; template <int TYPE>
; __device__ __forceinline__ void pass3_item(const KArgs& a, int l, int item, LAS unsigned char* lds) {
;     ...
;     const float gain = ((const float*)a.in[TYPE ? 7 : 5])[l * 128 + wid * 16 + fr];
;     bf16_t* mix = (bf16_t*)(wsb + WS_XN);
;     float gtv[4][4];
; #pragma unroll
;     for (int it = 0; it < 4; ++it)
; #pragma unroll
;         for (int r = 0; r < 4; ++r) gtv[it][r] = bf2f(u[(tok0 + it * 16 + fq * 4 + r) * DINP + (TYPE ? C_HG : C_GG) + h * 128 + wid * 16 + fr]);
.LBB0_509:
	s_or_b64 exec, exec, s[8:9]
	v_readlane_b32 s4, v255, 29
	v_readlane_b32 s40, v253, 48
	v_readlane_b32 s50, v253, 58
	v_add_u32_e32 v12, s4, v52
	v_or_b32_e32 v12, v12, v67
	v_ashrrev_i32_e32 v13, 31, v12
	v_readlane_b32 s51, v253, 59
	v_readlane_b32 s6, v255, 31
	v_readlane_b32 s8, v255, 33
	v_lshl_add_u64 v[12:13], v[12:13], 2, s[50:51]
	v_readlane_b32 s7, v255, 32
	s_waitcnt lgkmcnt(0)
	s_barrier
	global_load_dword v54, v[12:13], off
	v_or_b32_e32 v12, s8, v63
	v_mov_b64_e32 v[50:51], s[6:7]
	s_movk_i32 s2, 0x2a00
	v_readlane_b32 s9, v255, 34
	v_mad_u64_u32 v[14:15], s[6:7], v12, s2, v[50:51]
	s_mul_i32 s4, s9, 0x2a00
	v_readlane_b32 s6, v255, 35
	v_ashrrev_i32_e32 v53, 31, v52
	v_add_u32_e32 v15, s4, v15
	s_lshl_b32 s72, s6, 1
	v_lshl_add_u64 v[14:15], v[14:15], 0, s[72:73]
	v_lshlrev_b64 v[24:25], 1, v[52:53]
	v_lshl_add_u64 v[14:15], v[14:15], 0, v[24:25]
	v_lshlrev_b32_e32 v112, 1, v67
	v_lshl_add_u64 v[14:15], v[14:15], 0, v[112:113]
	global_load_ushort v142, v[14:15], off offset:2112
	v_readlane_b32 s7, v255, 36
	v_or_b32_e32 v46, 2, v12
	v_or_b32_e32 v48, 3, v12
	v_or_b32_e32 v67, 16, v63
	v_or_b32_e32 v44, s8, v67
	v_or_b32_e32 v42, 17, v12
	v_or_b32_e32 v40, 18, v12
	v_or_b32_e32 v28, 19, v12
	v_or_b32_e32 v60, 32, v63
	v_or_b32_e32 v26, s8, v60
	v_or_b32_e32 v30, 33, v12
	v_or_b32_e32 v36, 34, v12
	v_or_b32_e32 v38, 35, v12
	v_or_b32_e32 v56, 48, v63
	v_or_b32_e32 v22, s8, v56
	v_or_b32_e32 v20, 49, v12
	v_or_b32_e32 v18, 50, v12
	v_readlane_b32 s74, v255, 20
	v_mov_b32_e32 v13, s9
	v_mov_b32_e32 v15, s9
	v_mov_b32_e32 v47, s9
	v_mov_b32_e32 v49, s9
	v_mov_b32_e32 v45, s9
	v_mov_b32_e32 v43, s9
	v_mov_b32_e32 v41, s9
	v_mov_b32_e32 v29, s9
	v_mov_b32_e32 v27, s9
	v_mov_b32_e32 v31, s9
	v_mov_b32_e32 v37, s9
	v_mov_b32_e32 v39, s9
	v_mov_b32_e32 v23, s9
	v_mov_b32_e32 v21, s9
	v_mov_b32_e32 v19, s9
	v_readlane_b32 s68, v255, 16
	v_readlane_b32 s70, v255, 18
	v_readlane_b32 s41, v253, 49
	v_readlane_b32 s46, v253, 54
	v_readlane_b32 s47, v253, 55
	v_readlane_b32 s48, v253, 56
	v_readlane_b32 s49, v253, 57
	v_readlane_b32 s54, v253, 62
	v_readlane_b32 s55, v253, 63
	v_readlane_b32 s69, v255, 17
	v_readlane_b32 s71, v255, 19
	s_movk_i32 s66, 0x80
	s_movk_i32 s67, 0x100
	s_movk_i32 s3, 0x90
	v_readlane_b32 s42, v253, 50
	v_readlane_b32 s43, v253, 51
	v_readlane_b32 s44, v253, 52
	v_readlane_b32 s45, v253, 53
	v_readlane_b32 s52, v253, 60
	v_readlane_b32 s53, v253, 61


; __device__ __forceinline__ float bf2f(unsigned v) { return __uint_as_float(v << 16); }
; template <int TYPE>
; __device__ __forceinline__ void pass3_item(const KArgs& a, int l, int item, LAS unsigned char* lds) {
;     ...
;     const float gain = ((const float*)a.in[TYPE ? 7 : 5])[l * 128 + wid * 16 + fr];
;     bf16_t* mix = (bf16_t*)(wsb + WS_XN);
;     float gtv[4][4];
; #pragma unroll
;     for (int it = 0; it < 4; ++it)
; #pragma unroll
;         for (int r = 0; r < 4; ++r) gtv[it][r] = bf2f(u[(tok0 + it * 16 + fq * 4 + r) * DINP + (TYPE ? C_HG : C_GG) + h * 128 + wid * 16 + fr]);
	v_or_b32_e32 v14, 1, v12
	v_mad_u64_u32 v[16:17], s[6:7], v14, s2, v[50:51]
	v_add_u32_e32 v17, s4, v17
	v_lshl_add_u64 v[16:17], v[16:17], 0, s[72:73]
	v_lshl_add_u64 v[16:17], v[16:17], 0, v[24:25]
	v_lshl_add_u64 v[16:17], v[16:17], 0, v[112:113]
	global_load_ushort v143, v[16:17], off offset:2112


; __device__ __forceinline__ float bf2f(unsigned v) { return __uint_as_float(v << 16); }
; template <int TYPE>
; __device__ __forceinline__ void pass3_item(const KArgs& a, int l, int item, LAS unsigned char* lds) {
;     ...
;     const float gain = ((const float*)a.in[TYPE ? 7 : 5])[l * 128 + wid * 16 + fr];
;     bf16_t* mix = (bf16_t*)(wsb + WS_XN);
;     float gtv[4][4];
; #pragma unroll
;     for (int it = 0; it < 4; ++it)
; #pragma unroll
;         for (int r = 0; r < 4; ++r) gtv[it][r] = bf2f(u[(tok0 + it * 16 + fq * 4 + r) * DINP + (TYPE ? C_HG : C_GG) + h * 128 + wid * 16 + fr]);
	v_mad_u64_u32 v[16:17], s[6:7], v46, s2, v[50:51]
	v_add_u32_e32 v17, s4, v17
	v_lshl_add_u64 v[16:17], v[16:17], 0, s[72:73]
	v_lshl_add_u64 v[16:17], v[16:17], 0, v[24:25]
	v_lshl_add_u64 v[16:17], v[16:17], 0, v[112:113]
	global_load_ushort v144, v[16:17], off offset:2112


; __device__ __forceinline__ float bf2f(unsigned v) { return __uint_as_float(v << 16); }
; template <int TYPE>
; __device__ __forceinline__ void pass3_item(const KArgs& a, int l, int item, LAS unsigned char* lds) {
;     ...
;     const float gain = ((const float*)a.in[TYPE ? 7 : 5])[l * 128 + wid * 16 + fr];
;     bf16_t* mix = (bf16_t*)(wsb + WS_XN);
;     float gtv[4][4];
; #pragma unroll
;     for (int it = 0; it < 4; ++it)
; #pragma unroll
;         for (int r = 0; r < 4; ++r) gtv[it][r] = bf2f(u[(tok0 + it * 16 + fq * 4 + r) * DINP + (TYPE ? C_HG : C_GG) + h * 128 + wid * 16 + fr]);
	v_mad_u64_u32 v[16:17], s[6:7], v48, s2, v[50:51]
	v_add_u32_e32 v17, s4, v17
	v_lshl_add_u64 v[16:17], v[16:17], 0, s[72:73]
	v_lshl_add_u64 v[16:17], v[16:17], 0, v[24:25]
	v_lshl_add_u64 v[16:17], v[16:17], 0, v[112:113]
	global_load_ushort v145, v[16:17], off offset:2112


; __device__ __forceinline__ float bf2f(unsigned v) { return __uint_as_float(v << 16); }
; template <int TYPE>
; __device__ __forceinline__ void pass3_item(const KArgs& a, int l, int item, LAS unsigned char* lds) {
;     ...
;     const float gain = ((const float*)a.in[TYPE ? 7 : 5])[l * 128 + wid * 16 + fr];
;     bf16_t* mix = (bf16_t*)(wsb + WS_XN);
;     float gtv[4][4];
; #pragma unroll
;     for (int it = 0; it < 4; ++it)
; #pragma unroll
;         for (int r = 0; r < 4; ++r) gtv[it][r] = bf2f(u[(tok0 + it * 16 + fq * 4 + r) * DINP + (TYPE ? C_HG : C_GG) + h * 128 + wid * 16 + fr]);
	v_mad_u64_u32 v[16:17], s[6:7], v44, s2, v[50:51]
	v_add_u32_e32 v17, s4, v17
	v_lshl_add_u64 v[16:17], v[16:17], 0, s[72:73]
	v_lshl_add_u64 v[16:17], v[16:17], 0, v[24:25]
	v_lshl_add_u64 v[16:17], v[16:17], 0, v[112:113]
	global_load_ushort v146, v[16:17], off offset:2112


; __device__ __forceinline__ float bf2f(unsigned v) { return __uint_as_float(v << 16); }
; template <int TYPE>
; __device__ __forceinline__ void pass3_item(const KArgs& a, int l, int item, LAS unsigned char* lds) {
;     ...
;     const float gain = ((const float*)a.in[TYPE ? 7 : 5])[l * 128 + wid * 16 + fr];
;     bf16_t* mix = (bf16_t*)(wsb + WS_XN);
;     float gtv[4][4];
; #pragma unroll
;     for (int it = 0; it < 4; ++it)
; #pragma unroll
;         for (int r = 0; r < 4; ++r) gtv[it][r] = bf2f(u[(tok0 + it * 16 + fq * 4 + r) * DINP + (TYPE ? C_HG : C_GG) + h * 128 + wid * 16 + fr]);
	v_mad_u64_u32 v[16:17], s[6:7], v42, s2, v[50:51]
	v_add_u32_e32 v17, s4, v17
	v_lshl_add_u64 v[16:17], v[16:17], 0, s[72:73]
	v_lshl_add_u64 v[16:17], v[16:17], 0, v[24:25]
	v_lshl_add_u64 v[16:17], v[16:17], 0, v[112:113]
	global_load_ushort v147, v[16:17], off offset:2112


; __device__ __forceinline__ float bf2f(unsigned v) { return __uint_as_float(v << 16); }
; template <int TYPE>
; __device__ __forceinline__ void pass3_item(const KArgs& a, int l, int item, LAS unsigned char* lds) {
;     ...
;     const float gain = ((const float*)a.in[TYPE ? 7 : 5])[l * 128 + wid * 16 + fr];
;     bf16_t* mix = (bf16_t*)(wsb + WS_XN);
;     float gtv[4][4];
; #pragma unroll
;     for (int it = 0; it < 4; ++it)
; #pragma unroll
;         for (int r = 0; r < 4; ++r) gtv[it][r] = bf2f(u[(tok0 + it * 16 + fq * 4 + r) * DINP + (TYPE ? C_HG : C_GG) + h * 128 + wid * 16 + fr]);
	v_mad_u64_u32 v[16:17], s[6:7], v40, s2, v[50:51]
	v_add_u32_e32 v17, s4, v17
	v_lshl_add_u64 v[16:17], v[16:17], 0, s[72:73]
	v_lshl_add_u64 v[16:17], v[16:17], 0, v[24:25]
	v_lshl_add_u64 v[16:17], v[16:17], 0, v[112:113]
	global_load_ushort v148, v[16:17], off offset:2112


; __device__ __forceinline__ float bf2f(unsigned v) { return __uint_as_float(v << 16); }
; template <int TYPE>
; __device__ __forceinline__ void pass3_item(const KArgs& a, int l, int item, LAS unsigned char* lds) {
;     ...
;     const float gain = ((const float*)a.in[TYPE ? 7 : 5])[l * 128 + wid * 16 + fr];
;     bf16_t* mix = (bf16_t*)(wsb + WS_XN);
;     float gtv[4][4];
; #pragma unroll
;     for (int it = 0; it < 4; ++it)
; #pragma unroll
;         for (int r = 0; r < 4; ++r) gtv[it][r] = bf2f(u[(tok0 + it * 16 + fq * 4 + r) * DINP + (TYPE ? C_HG : C_GG) + h * 128 + wid * 16 + fr]);
	v_mad_u64_u32 v[16:17], s[6:7], v28, s2, v[50:51]
	v_add_u32_e32 v17, s4, v17
	v_lshl_add_u64 v[16:17], v[16:17], 0, s[72:73]
	v_lshl_add_u64 v[16:17], v[16:17], 0, v[24:25]
	v_lshl_add_u64 v[16:17], v[16:17], 0, v[112:113]
	global_load_ushort v149, v[16:17], off offset:2112


; __device__ __forceinline__ float bf2f(unsigned v) { return __uint_as_float(v << 16); }
; template <int TYPE>
; __device__ __forceinline__ void pass3_item(const KArgs& a, int l, int item, LAS unsigned char* lds) {
;     ...
;     const float gain = ((const float*)a.in[TYPE ? 7 : 5])[l * 128 + wid * 16 + fr];
;     bf16_t* mix = (bf16_t*)(wsb + WS_XN);
;     float gtv[4][4];
; #pragma unroll
;     for (int it = 0; it < 4; ++it)
; #pragma unroll
;         for (int r = 0; r < 4; ++r) gtv[it][r] = bf2f(u[(tok0 + it * 16 + fq * 4 + r) * DINP + (TYPE ? C_HG : C_GG) + h * 128 + wid * 16 + fr]);
	v_mad_u64_u32 v[16:17], s[6:7], v26, s2, v[50:51]
	v_add_u32_e32 v17, s4, v17
	v_lshl_add_u64 v[16:17], v[16:17], 0, s[72:73]
	v_lshl_add_u64 v[16:17], v[16:17], 0, v[24:25]
	v_lshl_add_u64 v[16:17], v[16:17], 0, v[112:113]
	global_load_ushort v150, v[16:17], off offset:2112


; __device__ __forceinline__ float bf2f(unsigned v) { return __uint_as_float(v << 16); }
; template <int TYPE>
; __device__ __forceinline__ void pass3_item(const KArgs& a, int l, int item, LAS unsigned char* lds) {
;     ...
;     const float gain = ((const float*)a.in[TYPE ? 7 : 5])[l * 128 + wid * 16 + fr];
;     bf16_t* mix = (bf16_t*)(wsb + WS_XN);
;     float gtv[4][4];
; #pragma unroll
;     for (int it = 0; it < 4; ++it)
; #pragma unroll
;         for (int r = 0; r < 4; ++r) gtv[it][r] = bf2f(u[(tok0 + it * 16 + fq * 4 + r) * DINP + (TYPE ? C_HG : C_GG) + h * 128 + wid * 16 + fr]);
	v_mad_u64_u32 v[16:17], s[6:7], v30, s2, v[50:51]
	v_add_u32_e32 v17, s4, v17
	v_lshl_add_u64 v[16:17], v[16:17], 0, s[72:73]
	v_lshl_add_u64 v[16:17], v[16:17], 0, v[24:25]
	v_lshl_add_u64 v[16:17], v[16:17], 0, v[112:113]
	global_load_ushort v151, v[16:17], off offset:2112


; __device__ __forceinline__ float bf2f(unsigned v) { return __uint_as_float(v << 16); }
; template <int TYPE>
; __device__ __forceinline__ void pass3_item(const KArgs& a, int l, int item, LAS unsigned char* lds) {
;     ...
;     const float gain = ((const float*)a.in[TYPE ? 7 : 5])[l * 128 + wid * 16 + fr];
;     bf16_t* mix = (bf16_t*)(wsb + WS_XN);
;     float gtv[4][4];
; #pragma unroll
;     for (int it = 0; it < 4; ++it)
; #pragma unroll
;         for (int r = 0; r < 4; ++r) gtv[it][r] = bf2f(u[(tok0 + it * 16 + fq * 4 + r) * DINP + (TYPE ? C_HG : C_GG) + h * 128 + wid * 16 + fr]);
	v_mad_u64_u32 v[16:17], s[6:7], v36, s2, v[50:51]
	v_add_u32_e32 v17, s4, v17
	v_lshl_add_u64 v[16:17], v[16:17], 0, s[72:73]
	v_lshl_add_u64 v[16:17], v[16:17], 0, v[24:25]
	v_lshl_add_u64 v[16:17], v[16:17], 0, v[112:113]
	global_load_ushort v152, v[16:17], off offset:2112


; __device__ __forceinline__ float bf2f(unsigned v) { return __uint_as_float(v << 16); }
; template <int TYPE>
; __device__ __forceinline__ void pass3_item(const KArgs& a, int l, int item, LAS unsigned char* lds) {
;     ...
;     const float gain = ((const float*)a.in[TYPE ? 7 : 5])[l * 128 + wid * 16 + fr];
;     bf16_t* mix = (bf16_t*)(wsb + WS_XN);
;     float gtv[4][4];
; #pragma unroll
;     for (int it = 0; it < 4; ++it)
; #pragma unroll
;         for (int r = 0; r < 4; ++r) gtv[it][r] = bf2f(u[(tok0 + it * 16 + fq * 4 + r) * DINP + (TYPE ? C_HG : C_GG) + h * 128 + wid * 16 + fr]);
	v_mad_u64_u32 v[16:17], s[6:7], v38, s2, v[50:51]
	v_add_u32_e32 v17, s4, v17
	v_lshl_add_u64 v[16:17], v[16:17], 0, s[72:73]
	v_lshl_add_u64 v[16:17], v[16:17], 0, v[24:25]
	v_lshl_add_u64 v[16:17], v[16:17], 0, v[112:113]
	global_load_ushort v153, v[16:17], off offset:2112


; __device__ __forceinline__ float bf2f(unsigned v) { return __uint_as_float(v << 16); }
; template <int TYPE>
; __device__ __forceinline__ void pass3_item(const KArgs& a, int l, int item, LAS unsigned char* lds) {
;     ...
;     const float gain = ((const float*)a.in[TYPE ? 7 : 5])[l * 128 + wid * 16 + fr];
;     bf16_t* mix = (bf16_t*)(wsb + WS_XN);
;     float gtv[4][4];
; #pragma unroll
;     for (int it = 0; it < 4; ++it)
; #pragma unroll
;         for (int r = 0; r < 4; ++r) gtv[it][r] = bf2f(u[(tok0 + it * 16 + fq * 4 + r) * DINP + (TYPE ? C_HG : C_GG) + h * 128 + wid * 16 + fr]);
	v_mad_u64_u32 v[16:17], s[6:7], v22, s2, v[50:51]
	v_add_u32_e32 v17, s4, v17
	v_lshl_add_u64 v[16:17], v[16:17], 0, s[72:73]
	v_lshl_add_u64 v[16:17], v[16:17], 0, v[24:25]
	v_lshl_add_u64 v[16:17], v[16:17], 0, v[112:113]
	global_load_ushort v154, v[16:17], off offset:2112


; __device__ __forceinline__ float bf2f(unsigned v) { return __uint_as_float(v << 16); }
; template <int TYPE>
; __device__ __forceinline__ void pass3_item(const KArgs& a, int l, int item, LAS unsigned char* lds) {
;     ...
;     const float gain = ((const float*)a.in[TYPE ? 7 : 5])[l * 128 + wid * 16 + fr];
;     bf16_t* mix = (bf16_t*)(wsb + WS_XN);
;     float gtv[4][4];
; #pragma unroll
;     for (int it = 0; it < 4; ++it)
; #pragma unroll
;         for (int r = 0; r < 4; ++r) gtv[it][r] = bf2f(u[(tok0 + it * 16 + fq * 4 + r) * DINP + (TYPE ? C_HG : C_GG) + h * 128 + wid * 16 + fr]);
	v_mad_u64_u32 v[16:17], s[6:7], v20, s2, v[50:51]
	v_add_u32_e32 v17, s4, v17
	v_lshl_add_u64 v[16:17], v[16:17], 0, s[72:73]
	v_lshl_add_u64 v[16:17], v[16:17], 0, v[24:25]
	v_lshl_add_u64 v[16:17], v[16:17], 0, v[112:113]
	global_load_ushort v155, v[16:17], off offset:2112


; __device__ __forceinline__ float bf2f(unsigned v) { return __uint_as_float(v << 16); }
; template <int TYPE>
; __device__ __forceinline__ void pass3_item(const KArgs& a, int l, int item, LAS unsigned char* lds) {
;     ...
;     const float gain = ((const float*)a.in[TYPE ? 7 : 5])[l * 128 + wid * 16 + fr];
;     bf16_t* mix = (bf16_t*)(wsb + WS_XN);
;     float gtv[4][4];
; #pragma unroll
;     for (int it = 0; it < 4; ++it)
; #pragma unroll
;         for (int r = 0; r < 4; ++r) gtv[it][r] = bf2f(u[(tok0 + it * 16 + fq * 4 + r) * DINP + (TYPE ? C_HG : C_GG) + h * 128 + wid * 16 + fr]);
	v_mad_u64_u32 v[16:17], s[6:7], v18, s2, v[50:51]
	v_add_u32_e32 v17, s4, v17
	v_lshl_add_u64 v[16:17], v[16:17], 0, s[72:73]
	v_lshl_add_u64 v[16:17], v[16:17], 0, v[24:25]
	v_lshl_add_u64 v[16:17], v[16:17], 0, v[112:113]
	global_load_ushort v156, v[16:17], off offset:2112
	v_mov_b32_e32 v17, s9

; __device__ __forceinline__ float bf2f(unsigned v) { return __uint_as_float(v << 16); }
; __device__ __forceinline__ unsigned f2bf(float f) { unsigned u = __float_as_uint(f); return (u + 0x7fffu + ((u >> 16) & 1u)) >> 16; }
; __device__ __forceinline__ float silu_(float z) { return z * sigmoid_(z); }
; template <int TYPE>
; __device__ __forceinline__ void pass3_item(const KArgs& a, int l, int item, LAS unsigned char* lds) {
;     ...
;     const float gain = ((const float*)a.in[TYPE ? 7 : 5])[l * 128 + wid * 16 + fr];
;     bf16_t* mix = (bf16_t*)(wsb + WS_XN);
;     float gtv[4][4];
; #pragma unroll
;     for (int it = 0; it < 4; ++it)
; #pragma unroll
;         for (int r = 0; r < 4; ++r) gtv[it][r] = bf2f(u[(tok0 + it * 16 + fq * 4 + r) * DINP + (TYPE ? C_HG : C_GG) + h * 128 + wid * 16 + fr]);
; #pragma unroll
;     for (int it = 0; it < 4; ++it)
; #pragma unroll
;         for (int r = 0; r < 4; ++r) { const int i = it * 16 + fq * 4 + r;
;             const float rstd = RSTD[i];
;             const float gt = gtv[it][r];
;             const float yv = o[it][r] * rstd * gain * silu_(gt);
;             mix[(tok0 + i) * DM + (TYPE ? 512 : 0) + h * 128 + wid * 16 + fr] = (bf16_t)f2bf(yv); }
	s_waitcnt vmcnt(0) lgkmcnt(0)
	v_lshlrev_b32_e32 v68, 16, v142
	v_lshlrev_b32_e32 v69, 16, v143
	v_lshlrev_b32_e32 v70, 16, v144
	v_lshlrev_b32_e32 v71, 16, v145
	v_lshlrev_b32_e32 v66, 16, v146
	v_lshlrev_b32_e32 v65, 16, v147
	v_lshlrev_b32_e32 v64, 16, v148
	v_lshlrev_b32_e32 v61, 16, v149
	v_lshlrev_b32_e32 v57, 16, v150
	v_lshlrev_b32_e32 v58, 16, v151
	v_lshlrev_b32_e32 v59, 16, v152
	v_lshlrev_b32_e32 v62, 16, v153
	v_lshlrev_b32_e32 v55, 16, v154
	v_lshlrev_b32_e32 v53, 16, v155
	v_lshlrev_b32_e32 v52, 16, v156
	v_or_b32_e32 v16, 51, v12
	v_mad_u64_u32 v[50:51], s[6:7], v16, s2, v[50:51]
	v_add_u32_e32 v51, s4, v51
	v_lshl_add_u64 v[50:51], v[50:51], 0, s[72:73]
	v_lshl_add_u64 v[50:51], v[50:51], 0, v[24:25]
	v_lshl_add_u64 v[50:51], v[50:51], 0, v[112:113]
	global_load_ushort v50, v[50:51], off offset:2112
	v_lshl_add_u32 v51, v63, 2, s74
	ds_read_b128 v[72:75], v51
	v_mul_f32_e32 v51, 0xbfb8aa3b, v68
	v_exp_f32_e32 v51, v51
	v_readlane_b32 s6, v255, 37
	v_readlane_b32 s7, v255, 38
	s_add_u32 s6, s6, s72
	v_add_f32_e32 v51, 1.0, v51
	v_rcp_f32_e32 v51, v51
	s_addc_u32 s7, s7, 0
	s_waitcnt lgkmcnt(0)
	v_mul_f32_e32 v32, v32, v72
	v_lshl_add_u64 v[24:25], s[6:7], 0, v[24:25]
	v_mul_f32_e32 v32, v54, v32
	v_mul_f32_e32 v51, v51, v68
	v_lshl_add_u64 v[24:25], v[24:25], 0, v[112:113]
	s_mov_b64 s[6:7], 0x6300000
	v_mul_f32_e32 v32, v51, v32
	v_lshl_add_u64 v[24:25], v[24:25], 0, s[6:7]
	v_bfe_u32 v51, v32, 16, 1
	v_lshlrev_b64 v[12:13], 12, v[12:13]
	v_add3_u32 v32, v32, v51, s1
	v_lshl_add_u64 v[12:13], v[24:25], 0, v[12:13]
	global_store_short_d16_hi v[12:13], v32, off
	v_mul_f32_e32 v13, 0xbfb8aa3b, v69
	v_exp_f32_e32 v13, v13
	v_mul_f32_e32 v12, v33, v73
	v_mul_f32_e32 v12, v54, v12
	v_readlane_b32 s4, v255, 30
	v_add_f32_e32 v13, 1.0, v13
	v_rcp_f32_e32 v13, v13
	s_add_i32 s4, s4, s70
	s_cmpk_gt_i32 s4, 0x7ff
	v_mul_f32_e32 v13, v13, v69
	v_mul_f32_e32 v12, v13, v12
	v_bfe_u32 v13, v12, 16, 1
	v_add3_u32 v32, v12, v13, s1
	v_lshlrev_b64 v[12:13], 12, v[14:15]
	v_lshl_add_u64 v[12:13], v[24:25], 0, v[12:13]
	global_store_short_d16_hi v[12:13], v32, off
	v_mul_f32_e32 v13, 0xbfb8aa3b, v70
	v_exp_f32_e32 v13, v13
	v_mul_f32_e32 v12, v34, v74
	v_mul_f32_e32 v12, v54, v12
	v_lshlrev_b64 v[32:33], 12, v[44:45]
	v_add_f32_e32 v13, 1.0, v13
	v_rcp_f32_e32 v13, v13
	v_lshl_add_u64 v[32:33], v[24:25], 0, v[32:33]
	v_mul_f32_e32 v13, v13, v70
	v_mul_f32_e32 v12, v13, v12
	v_bfe_u32 v13, v12, 16, 1
	v_add3_u32 v14, v12, v13, s1
	v_lshlrev_b64 v[12:13], 12, v[46:47]
	v_lshl_add_u64 v[12:13], v[24:25], 0, v[12:13]
	global_store_short_d16_hi v[12:13], v14, off
	v_mul_f32_e32 v13, 0xbfb8aa3b, v71
	v_exp_f32_e32 v13, v13
	v_mul_f32_e32 v12, v35, v75
	v_mul_f32_e32 v12, v54, v12
	v_add_f32_e32 v13, 1.0, v13
	v_rcp_f32_e32 v13, v13
	s_waitcnt vmcnt(0)
	v_lshlrev_b32_e32 v50, 16, v50
	v_mul_f32_e32 v13, v13, v71
	v_mul_f32_e32 v12, v13, v12
	v_bfe_u32 v13, v12, 16, 1
	v_add3_u32 v14, v12, v13, s1
	v_lshlrev_b64 v[12:13], 12, v[48:49]
	v_lshl_add_u64 v[12:13], v[24:25], 0, v[12:13]
	global_store_short_d16_hi v[12:13], v14, off
	v_lshl_add_u32 v12, v67, 2, s74
	ds_read_b128 v[12:15], v12
	s_waitcnt lgkmcnt(0)
	v_mul_f32_e32 v8, v8, v12
	v_mul_f32_e32 v12, 0xbfb8aa3b, v66
	v_exp_f32_e32 v12, v12
	v_mul_f32_e32 v8, v54, v8
	v_add_f32_e32 v12, 1.0, v12
	v_rcp_f32_e32 v12, v12
	s_nop 0
	v_mul_f32_e32 v12, v12, v66
	v_mul_f32_e32 v8, v12, v8
	v_bfe_u32 v12, v8, 16, 1
	v_add3_u32 v8, v8, v12, s1
	global_store_short_d16_hi v[32:33], v8, off
	v_mul_f32_e32 v8, v9, v13
	v_mul_f32_e32 v9, 0xbfb8aa3b, v65
	v_exp_f32_e32 v9, v9
	v_mul_f32_e32 v8, v54, v8
	v_add_f32_e32 v9, 1.0, v9
	v_rcp_f32_e32 v9, v9
	s_nop 0
	v_mul_f32_e32 v9, v9, v65
	v_mul_f32_e32 v8, v9, v8
	v_bfe_u32 v9, v8, 16, 1
	v_add3_u32 v12, v8, v9, s1
	v_lshlrev_b64 v[8:9], 12, v[42:43]
	v_lshl_add_u64 v[8:9], v[24:25], 0, v[8:9]
	global_store_short_d16_hi v[8:9], v12, off
	v_mul_f32_e32 v9, 0xbfb8aa3b, v64
	v_exp_f32_e32 v9, v9
	v_mul_f32_e32 v8, v10, v14
	v_mul_f32_e32 v8, v54, v8
	v_lshlrev_b64 v[12:13], 12, v[26:27]
	v_add_f32_e32 v9, 1.0, v9
	v_rcp_f32_e32 v9, v9
	v_lshl_add_u64 v[12:13], v[24:25], 0, v[12:13]
	v_mul_f32_e32 v9, v9, v64
	v_mul_f32_e32 v8, v9, v8
	v_bfe_u32 v9, v8, 16, 1
	v_add3_u32 v10, v8, v9, s1
	v_lshlrev_b64 v[8:9], 12, v[40:41]
	v_lshl_add_u64 v[8:9], v[24:25], 0, v[8:9]
	global_store_short_d16_hi v[8:9], v10, off
	v_mul_f32_e32 v9, 0xbfb8aa3b, v61
	v_exp_f32_e32 v9, v9
	v_mul_f32_e32 v8, v11, v15
	v_mul_f32_e32 v8, v54, v8
	v_add_f32_e32 v9, 1.0, v9
	v_rcp_f32_e32 v9, v9
	s_nop 0
	v_mul_f32_e32 v9, v9, v61
	v_mul_f32_e32 v8, v9, v8
	v_bfe_u32 v9, v8, 16, 1
	v_add3_u32 v10, v8, v9, s1
	v_lshlrev_b64 v[8:9], 12, v[28:29]
	v_lshl_add_u64 v[8:9], v[24:25], 0, v[8:9]
	global_store_short_d16_hi v[8:9], v10, off
	v_lshl_add_u32 v8, v60, 2, s74
	ds_read_b128 v[8:11], v8
	s_waitcnt lgkmcnt(0)
; __device__ __forceinline__ unsigned f2bf(float f) { unsigned u = __float_as_uint(f); return (u + 0x7fffu + ((u >> 16) & 1u)) >> 16; }
; __device__ __forceinline__ float silu_(float z) { return z * sigmoid_(z); }
; template <int TYPE>
; __device__ __forceinline__ void pass3_item(const KArgs& a, int l, int item, LAS unsigned char* lds) {
;     ...
;     for (int it = 0; it < 4; ++it)
; #pragma unroll
;         for (int r = 0; r < 4; ++r) { const int i = it * 16 + fq * 4 + r;
;             const float rstd = RSTD[i];
;             const float gt = gtv[it][r];
;             const float yv = o[it][r] * rstd * gain * silu_(gt);
;             mix[(tok0 + i) * DM + (TYPE ? 512 : 0) + h * 128 + wid * 16 + fr] = (bf16_t)f2bf(yv); }
	v_mul_f32_e32 v4, v4, v8
	v_mul_f32_e32 v8, 0xbfb8aa3b, v57
	v_exp_f32_e32 v8, v8
	v_mul_f32_e32 v4, v54, v4
	v_add_f32_e32 v8, 1.0, v8
	v_rcp_f32_e32 v8, v8
	s_nop 0
	v_mul_f32_e32 v8, v8, v57
	v_mul_f32_e32 v4, v8, v4
	v_bfe_u32 v8, v4, 16, 1
	v_add3_u32 v4, v4, v8, s1
	global_store_short_d16_hi v[12:13], v4, off
	v_mul_f32_e32 v4, v5, v9
	v_mul_f32_e32 v5, 0xbfb8aa3b, v58
	v_exp_f32_e32 v5, v5
	v_mul_f32_e32 v4, v54, v4
	v_add_f32_e32 v5, 1.0, v5
	v_rcp_f32_e32 v5, v5
	s_nop 0
	v_mul_f32_e32 v5, v5, v58
	v_mul_f32_e32 v4, v5, v4
	v_bfe_u32 v5, v4, 16, 1
	v_add3_u32 v8, v4, v5, s1
	v_lshlrev_b64 v[4:5], 12, v[30:31]
	v_lshl_add_u64 v[4:5], v[24:25], 0, v[4:5]
	global_store_short_d16_hi v[4:5], v8, off
	v_mul_f32_e32 v5, 0xbfb8aa3b, v59
	v_exp_f32_e32 v5, v5
	v_mul_f32_e32 v4, v6, v10
	v_mul_f32_e32 v4, v54, v4
	v_lshlrev_b64 v[8:9], 12, v[22:23]
	v_add_f32_e32 v5, 1.0, v5
	v_rcp_f32_e32 v5, v5
	v_lshl_add_u64 v[8:9], v[24:25], 0, v[8:9]
	v_mul_f32_e32 v5, v5, v59
	v_mul_f32_e32 v4, v5, v4
	v_bfe_u32 v5, v4, 16, 1
	v_add3_u32 v6, v4, v5, s1
	v_lshlrev_b64 v[4:5], 12, v[36:37]
	v_lshl_add_u64 v[4:5], v[24:25], 0, v[4:5]
	global_store_short_d16_hi v[4:5], v6, off
	v_mul_f32_e32 v5, 0xbfb8aa3b, v62
	v_exp_f32_e32 v5, v5
	v_mul_f32_e32 v4, v7, v11
	v_mul_f32_e32 v4, v54, v4
	v_add_f32_e32 v5, 1.0, v5
	v_rcp_f32_e32 v5, v5
	s_nop 0
	v_mul_f32_e32 v5, v5, v62
	v_mul_f32_e32 v4, v5, v4
	v_bfe_u32 v5, v4, 16, 1
	v_add3_u32 v6, v4, v5, s1
	v_lshlrev_b64 v[4:5], 12, v[38:39]
	v_lshl_add_u64 v[4:5], v[24:25], 0, v[4:5]
	global_store_short_d16_hi v[4:5], v6, off
	v_lshl_add_u32 v4, v56, 2, s74
	ds_read_b128 v[4:7], v4
	s_waitcnt lgkmcnt(0)
	v_mul_f32_e32 v0, v0, v4
	v_mul_f32_e32 v4, 0xbfb8aa3b, v55
	v_exp_f32_e32 v4, v4
	v_mul_f32_e32 v0, v54, v0
	v_add_f32_e32 v4, 1.0, v4
	v_rcp_f32_e32 v4, v4
	s_nop 0
	v_mul_f32_e32 v4, v4, v55
	v_mul_f32_e32 v0, v4, v0
	v_bfe_u32 v4, v0, 16, 1
	v_add3_u32 v0, v0, v4, s1
	global_store_short_d16_hi v[8:9], v0, off
	v_mul_f32_e32 v0, v1, v5
	v_mul_f32_e32 v1, 0xbfb8aa3b, v53
	v_exp_f32_e32 v1, v1
	v_mul_f32_e32 v0, v54, v0
	v_add_f32_e32 v1, 1.0, v1
	v_rcp_f32_e32 v1, v1
	s_nop 0
	v_mul_f32_e32 v1, v1, v53
	v_mul_f32_e32 v0, v1, v0
	v_bfe_u32 v1, v0, 16, 1
	v_add3_u32 v4, v0, v1, s1
	v_lshlrev_b64 v[0:1], 12, v[20:21]
	v_lshl_add_u64 v[0:1], v[24:25], 0, v[0:1]
	global_store_short_d16_hi v[0:1], v4, off
	v_mul_f32_e32 v1, 0xbfb8aa3b, v52
	v_exp_f32_e32 v1, v1
	v_mul_f32_e32 v0, v2, v6
	v_mul_f32_e32 v0, v54, v0
	v_add_f32_e32 v1, 1.0, v1
	v_rcp_f32_e32 v1, v1
	s_nop 0
	v_mul_f32_e32 v1, v1, v52
	v_mul_f32_e32 v0, v1, v0
	v_bfe_u32 v1, v0, 16, 1
	v_add3_u32 v2, v0, v1, s1
	v_lshlrev_b64 v[0:1], 12, v[18:19]
	v_lshl_add_u64 v[0:1], v[24:25], 0, v[0:1]
	global_store_short_d16_hi v[0:1], v2, off
	v_mul_f32_e32 v1, 0xbfb8aa3b, v50
	v_exp_f32_e32 v1, v1
	v_mul_f32_e32 v0, v3, v7
	v_mul_f32_e32 v0, v54, v0
	v_add_f32_e32 v1, 1.0, v1
	v_rcp_f32_e32 v1, v1
	s_nop 0
	v_mul_f32_e32 v1, v1, v50
	v_mul_f32_e32 v0, v1, v0
	v_bfe_u32 v1, v0, 16, 1
	v_add3_u32 v2, v0, v1, s1
	v_lshlrev_b64 v[0:1], 12, v[16:17]
	v_lshl_add_u64 v[0:1], v[24:25], 0, v[0:1]
	global_store_short_d16_hi v[0:1], v2, off
	s_cbranch_scc1 .LBB0_533
